# GLA cumulative decay: 64-lane DPP scan instead of six ds_bpermute rounds (a-tile and c-tile)
# speedup vs baseline: 1.0078x; 1.0078x over previous
; __device__ __forceinline__ float bflo(unsigned w) { return __uint_as_float(w << 16); }
; __device__ __forceinline__ float bfhi(unsigned w) { return __uint_as_float(w & 0xffff0000u); }
; __device__ __forceinline__ void gla_gcum(LAS unsigned char* lds, const GlaArgs& A, int t0, int h, int tid) {
;     ...
;     { const int d = tid & 63, i0 = tid >> 6; float au[16]; const float ab = A.abias[h * 64 + d];
; #pragma unroll
;       for (int j = 0; j < 16; ++j) au[j] = A.aup[j * 256 + h * 64 + d];
;       u32x4 al0[8], al1[8];
; #pragma unroll
;       for (int e = 0; e < 8; ++e) { const u32x4* ap = (const u32x4*)(A.Ug + (size_t)(t0 + i0 + 8 * e) * 1792 + 1024); al0[e] = ap[0]; al1[e] = ap[1]; }
; #pragma unroll
;       for (int e = 0; e < 8; ++e) { const int i = i0 + 8 * e; const u32x4 a0 = al0[e], a1 = al1[e];
;           float x = ab;
;           x += bflo(a0.x) * au[0] + bfhi(a0.x) * au[1] + bflo(a0.y) * au[2] + bfhi(a0.y) * au[3] + bflo(a0.z) * au[4] + bfhi(a0.z) * au[5] + bflo(a0.w) * au[6] + bfhi(a0.w) * au[7];
;           x += bflo(a1.x) * au[8] + bfhi(a1.x) * au[9] + bflo(a1.y) * au[10] + bfhi(a1.y) * au[11] + bflo(a1.z) * au[12] + bfhi(a1.z) * au[13] + bflo(a1.w) * au[14] + bfhi(a1.w) * au[15];
;           const float ls = fminf(x, 0.f) - __logf(1.f + __expf(-fabsf(x)));
;           GC[i * 65 + d] = ls * (1.0f / 16.0f); } }
.LBB0_192:
	v_add_u32_e32 v135, s29, v125
	v_mov_b64_e32 v[2:3], s[24:25]
	v_mad_i64_i32 v[4:5], s[20:21], v135, s80, v[2:3]
	global_load_dwordx4 v[10:13], v[4:5], off offset:2048
	global_load_dwordx4 v[14:17], v[4:5], off offset:2064
	global_load_dword v141, v[60:61], off offset:1024
	global_load_dword v117, v[60:61], off offset:2048
	global_load_dword v116, v[60:61], off offset:3072
	global_load_dword v114, v[62:63], off
	global_load_dword v113, v[64:65], off
	global_load_dword v112, v[66:67], off
	global_load_dword v111, v[68:69], off
	global_load_dword v143, v[60:61], off
	global_load_dword v110, v[72:73], off
	global_load_dword v109, v[74:75], off
	global_load_dword v108, v[76:77], off
	global_load_dword v107, v[78:79], off
	global_load_dword v106, v[80:81], off
	global_load_dword v105, v[82:83], off
	global_load_dword v104, v[84:85], off
	global_load_dword v115, v[70:71], off
	global_load_dword v142, v[58:59], off
	v_add_u32_e32 v103, 8, v135
	v_mad_i64_i32 v[4:5], s[20:21], v103, s80, v[2:3]
	global_load_dwordx4 v[50:53], v[4:5], off offset:2048
	global_load_dwordx4 v[54:57], v[4:5], off offset:2064
	v_add_u32_e32 v102, 16, v135
	v_add_u32_e32 v140, 24, v135
	v_add_u32_e32 v139, 32, v135
	v_add_u32_e32 v138, 40, v135
	v_add_u32_e32 v137, 48, v135
	v_add_u32_e32 v136, 56, v135
	v_mad_i64_i32 v[6:7], s[20:21], v102, s80, v[2:3]
	v_mad_i64_i32 v[8:9], s[20:21], v140, s80, v[2:3]
	v_mad_i64_i32 v[18:19], s[20:21], v139, s80, v[2:3]
	v_mad_i64_i32 v[22:23], s[20:21], v138, s80, v[2:3]
	v_mad_i64_i32 v[144:145], s[20:21], v137, s80, v[2:3]
	v_mad_i64_i32 v[146:147], s[20:21], v136, s80, v[2:3]
	global_load_dwordx4 v[42:45], v[6:7], off offset:2064
	global_load_dwordx4 v[46:49], v[6:7], off offset:2048
	global_load_dwordx4 v[34:37], v[8:9], off offset:2064
	global_load_dwordx4 v[38:41], v[8:9], off offset:2048
	global_load_dwordx4 v[26:29], v[18:19], off offset:2064
	global_load_dwordx4 v[30:33], v[18:19], off offset:2048
	s_nop 0
	global_load_dwordx4 v[18:21], v[22:23], off offset:2064
	s_nop 0
	global_load_dwordx4 v[22:25], v[22:23], off offset:2048
	s_nop 0
	global_load_dwordx4 v[2:5], v[144:145], off offset:2064
	global_load_dwordx4 v[6:9], v[144:145], off offset:2048
	s_waitcnt vmcnt(30)
	v_lshlrev_b32_e32 v144, 16, v10
	v_and_b32_e32 v10, 0xffff0000, v10
	s_waitcnt vmcnt(29)
	v_lshlrev_b32_e32 v150, 16, v14
	v_and_b32_e32 v14, 0xffff0000, v14
	s_waitcnt vmcnt(28)
	v_mul_f32_e32 v10, v141, v10
	v_lshlrev_b32_e32 v145, 16, v11
	v_and_b32_e32 v11, 0xffff0000, v11
	v_lshlrev_b32_e32 v151, 16, v15
	v_lshlrev_b32_e32 v148, 16, v12
	s_waitcnt vmcnt(21)
	v_fmac_f32_e32 v10, v143, v144
	s_waitcnt vmcnt(20)
	v_mul_f32_e32 v14, v110, v14
	v_fmac_f32_e32 v10, v117, v145
	v_and_b32_e32 v15, 0xffff0000, v15
	v_fmac_f32_e32 v10, v116, v11
	v_and_b32_e32 v12, 0xffff0000, v12
	v_lshlrev_b32_e32 v152, 16, v16
	v_fmac_f32_e32 v10, v114, v148
	s_waitcnt vmcnt(13)
	v_fmac_f32_e32 v14, v115, v150
	v_fmac_f32_e32 v14, v109, v151
	v_fmac_f32_e32 v14, v108, v15
	v_lshlrev_b32_e32 v149, 16, v13
	v_and_b32_e32 v16, 0xffff0000, v16
	v_fmac_f32_e32 v14, v107, v152
	v_fmac_f32_e32 v10, v113, v12
	v_and_b32_e32 v13, 0xffff0000, v13
	v_lshlrev_b32_e32 v153, 16, v17
	v_fmac_f32_e32 v14, v106, v16
	v_fmac_f32_e32 v10, v112, v149
	v_and_b32_e32 v17, 0xffff0000, v17
	v_fmac_f32_e32 v14, v105, v153
	v_fmac_f32_e32 v10, v111, v13
	v_fmac_f32_e32 v14, v104, v17
	s_waitcnt vmcnt(12)
	v_add_f32_e32 v10, v142, v10
	v_add_f32_e32 v144, v10, v14
	v_mul_f32_e64 v10, |v144|, s77
	v_exp_f32_e32 v145, v10
	global_load_dwordx4 v[10:13], v[146:147], off offset:2064
	global_load_dwordx4 v[14:17], v[146:147], off offset:2048
	s_waitcnt vmcnt(13)
	v_lshlrev_b32_e32 v146, 16, v50
	v_and_b32_e32 v50, 0xffff0000, v50
	v_mul_f32_e32 v50, v141, v50
	v_fmac_f32_e32 v50, v143, v146
	v_lshlrev_b32_e32 v146, 16, v51
	v_fmac_f32_e32 v50, v117, v146
	v_and_b32_e32 v51, 0xffff0000, v51
	v_fmac_f32_e32 v50, v116, v51
	v_lshlrev_b32_e32 v51, 16, v52
	v_fmac_f32_e32 v50, v114, v51
	v_and_b32_e32 v51, 0xffff0000, v52
	v_fmac_f32_e32 v50, v113, v51
	v_lshlrev_b32_e32 v51, 16, v53
	v_fmac_f32_e32 v50, v112, v51
	v_and_b32_e32 v51, 0xffff0000, v53
	s_waitcnt vmcnt(12)
	v_and_b32_e32 v52, 0xffff0000, v54
	v_fmac_f32_e32 v50, v111, v51
	v_lshlrev_b32_e32 v51, 16, v54
	v_mul_f32_e32 v52, v110, v52
	v_fmac_f32_e32 v52, v115, v51
	v_lshlrev_b32_e32 v51, 16, v55
	v_fmac_f32_e32 v52, v109, v51
	v_and_b32_e32 v51, 0xffff0000, v55
	v_add_f32_e32 v145, 1.0, v145
	v_fmac_f32_e32 v52, v108, v51
	v_lshlrev_b32_e32 v51, 16, v56
	v_cmp_gt_f32_e64 s[20:21], s76, v145
	v_fmac_f32_e32 v52, v107, v51
	v_and_b32_e32 v51, 0xffff0000, v56
	v_cndmask_b32_e64 v147, 0, 32, s[20:21]
	v_fmac_f32_e32 v52, v106, v51
	v_lshlrev_b32_e32 v51, 16, v57
	v_ldexp_f32 v145, v145, v147
	v_fmac_f32_e32 v52, v105, v51
	v_and_b32_e32 v51, 0xffff0000, v57
	v_log_f32_e32 v145, v145
	v_add_f32_e32 v50, v142, v50
	v_fmac_f32_e32 v52, v104, v51
	v_add_f32_e32 v50, v50, v52
	v_mul_f32_e64 v51, |v50|, s77
	v_exp_f32_e32 v51, v51
	v_mul_f32_e32 v148, 0x3f317217, v145
	v_fma_f32 v148, v145, s81, -v148
	v_fmac_f32_e32 v148, 0x3377d1cf, v145
	v_cndmask_b32_e64 v147, 0, v238, s[20:21]
	v_fmac_f32_e32 v148, 0x3f317217, v145
	v_cmp_lt_f32_e64 s[20:21], |v145|, s82
	v_add_f32_e32 v51, 1.0, v51
	v_min_f32_e32 v144, 0, v144
	v_cndmask_b32_e64 v145, v145, v148, s[20:21]
	v_cmp_gt_f32_e64 s[20:21], s76, v51
	v_sub_f32_e32 v52, v145, v147
	v_sub_f32_e32 v52, v144, v52
	v_cndmask_b32_e64 v53, 0, 32, s[20:21]
	v_ldexp_f32 v51, v51, v53
	v_log_f32_e32 v51, v51
	v_mul_f32_e32 v52, 0x3d800000, v52
	v_add_u32_e32 v53, v119, v120
	ds_write_b32 v53, v52
	v_mul_f32_e32 v52, 0x3f317217, v51
	v_fma_f32 v52, v51, s81, -v52
	v_fmac_f32_e32 v52, 0x3377d1cf, v51
	v_fmac_f32_e32 v52, 0x3f317217, v51
	v_cmp_lt_f32_e64 s[22:23], |v51|, s82
	v_min_f32_e32 v50, 0, v50
	s_nop 0
	v_cndmask_b32_e64 v51, v51, v52, s[22:23]
	s_waitcnt vmcnt(10)
; __device__ __forceinline__ float bflo(unsigned w) { return __uint_as_float(w << 16); }
; __device__ __forceinline__ float bfhi(unsigned w) { return __uint_as_float(w & 0xffff0000u); }
; __device__ __forceinline__ void gla_gcum(LAS unsigned char* lds, const GlaArgs& A, int t0, int h, int tid) {
;     ...
;       for (int e = 0; e < 8; ++e) { const int i = i0 + 8 * e; const u32x4 a0 = al0[e], a1 = al1[e];
;           float x = ab;
;           x += bflo(a0.x) * au[0] + bfhi(a0.x) * au[1] + bflo(a0.y) * au[2] + bfhi(a0.y) * au[3] + bflo(a0.z) * au[4] + bfhi(a0.z) * au[5] + bflo(a0.w) * au[6] + bfhi(a0.w) * au[7];
;           x += bflo(a1.x) * au[8] + bfhi(a1.x) * au[9] + bflo(a1.y) * au[10] + bfhi(a1.y) * au[11] + bflo(a1.z) * au[12] + bfhi(a1.z) * au[13] + bflo(a1.w) * au[14] + bfhi(a1.w) * au[15];
;           const float ls = fminf(x, 0.f) - __logf(1.f + __expf(-fabsf(x)));
;           GC[i * 65 + d] = ls * (1.0f / 16.0f); } }
	v_lshlrev_b32_e32 v52, 16, v46
	v_and_b32_e32 v46, 0xffff0000, v46
	v_mul_f32_e32 v46, v141, v46
	v_fmac_f32_e32 v46, v143, v52
	v_lshlrev_b32_e32 v52, 16, v47
	v_fmac_f32_e32 v46, v117, v52
	v_and_b32_e32 v47, 0xffff0000, v47
	v_fmac_f32_e32 v46, v116, v47
	v_lshlrev_b32_e32 v47, 16, v48
	v_fmac_f32_e32 v46, v114, v47
	v_and_b32_e32 v47, 0xffff0000, v48
	v_fmac_f32_e32 v46, v113, v47
	v_lshlrev_b32_e32 v47, 16, v49
	v_fmac_f32_e32 v46, v112, v47
	v_and_b32_e32 v47, 0xffff0000, v49
	v_fmac_f32_e32 v46, v111, v47
	v_lshlrev_b32_e32 v47, 16, v42
	v_and_b32_e32 v42, 0xffff0000, v42
	v_mul_f32_e32 v42, v110, v42
	v_fmac_f32_e32 v42, v115, v47
	v_lshlrev_b32_e32 v47, 16, v43
	v_fmac_f32_e32 v42, v109, v47
	v_and_b32_e32 v43, 0xffff0000, v43
	v_fmac_f32_e32 v42, v108, v43
	v_lshlrev_b32_e32 v43, 16, v44
	v_fmac_f32_e32 v42, v107, v43
	v_and_b32_e32 v43, 0xffff0000, v44
	v_fmac_f32_e32 v42, v106, v43
	v_lshlrev_b32_e32 v43, 16, v45
	v_fmac_f32_e32 v42, v105, v43
	v_and_b32_e32 v43, 0xffff0000, v45
	v_add_f32_e32 v46, v142, v46
	v_fmac_f32_e32 v42, v104, v43
	v_add_f32_e32 v42, v46, v42
	v_mul_f32_e64 v43, |v42|, s77
	v_exp_f32_e32 v43, v43
	v_cndmask_b32_e64 v44, 0, v238, s[20:21]
	v_sub_f32_e32 v44, v51, v44
	v_sub_f32_e32 v44, v50, v44
	v_add_f32_e32 v43, 1.0, v43
	v_cmp_gt_f32_e64 s[20:21], s76, v43
	v_mul_f32_e32 v44, 0x3d800000, v44
	ds_write_b32 v53, v44 offset:2080
	v_cndmask_b32_e64 v45, 0, 32, s[20:21]
	v_ldexp_f32 v43, v43, v45
	v_log_f32_e32 v43, v43
	v_min_f32_e32 v42, 0, v42
	v_mul_f32_e32 v44, 0x3f317217, v43
	v_fma_f32 v44, v43, s81, -v44
	v_fmac_f32_e32 v44, 0x3377d1cf, v43
	v_fmac_f32_e32 v44, 0x3f317217, v43
	v_cmp_lt_f32_e64 s[22:23], |v43|, s82
	s_nop 1
	v_cndmask_b32_e64 v43, v43, v44, s[22:23]
	s_waitcnt vmcnt(8)
	v_lshlrev_b32_e32 v44, 16, v38
	v_and_b32_e32 v38, 0xffff0000, v38
	v_mul_f32_e32 v38, v141, v38
	v_fmac_f32_e32 v38, v143, v44
	v_lshlrev_b32_e32 v44, 16, v39
	v_fmac_f32_e32 v38, v117, v44
	v_and_b32_e32 v39, 0xffff0000, v39
	v_fmac_f32_e32 v38, v116, v39
	v_lshlrev_b32_e32 v39, 16, v40
	v_fmac_f32_e32 v38, v114, v39
	v_and_b32_e32 v39, 0xffff0000, v40
	v_fmac_f32_e32 v38, v113, v39
	v_lshlrev_b32_e32 v39, 16, v41
	v_fmac_f32_e32 v38, v112, v39
	v_and_b32_e32 v39, 0xffff0000, v41
	v_fmac_f32_e32 v38, v111, v39
	v_lshlrev_b32_e32 v39, 16, v34
	v_and_b32_e32 v34, 0xffff0000, v34
	v_mul_f32_e32 v34, v110, v34
	v_fmac_f32_e32 v34, v115, v39
	v_lshlrev_b32_e32 v39, 16, v35
	v_fmac_f32_e32 v34, v109, v39
	v_and_b32_e32 v35, 0xffff0000, v35
	v_fmac_f32_e32 v34, v108, v35
	v_lshlrev_b32_e32 v35, 16, v36
	v_fmac_f32_e32 v34, v107, v35
	v_and_b32_e32 v35, 0xffff0000, v36
	v_fmac_f32_e32 v34, v106, v35
	v_lshlrev_b32_e32 v35, 16, v37
	v_fmac_f32_e32 v34, v105, v35
	v_and_b32_e32 v35, 0xffff0000, v37
	v_add_f32_e32 v38, v142, v38
	v_fmac_f32_e32 v34, v104, v35
	v_add_f32_e32 v34, v38, v34
	v_mul_f32_e64 v35, |v34|, s77
	v_exp_f32_e32 v35, v35
	v_cndmask_b32_e64 v36, 0, v238, s[20:21]
	v_sub_f32_e32 v36, v43, v36
	v_sub_f32_e32 v36, v42, v36
	v_add_f32_e32 v35, 1.0, v35
	v_cmp_gt_f32_e64 s[20:21], s76, v35
	v_mul_f32_e32 v36, 0x3d800000, v36
	ds_write_b32 v53, v36 offset:4160
	v_cndmask_b32_e64 v37, 0, 32, s[20:21]
	v_ldexp_f32 v35, v35, v37
	v_log_f32_e32 v35, v35
	v_min_f32_e32 v34, 0, v34
	v_mul_f32_e32 v36, 0x3f317217, v35
	v_fma_f32 v36, v35, s81, -v36
	v_fmac_f32_e32 v36, 0x3377d1cf, v35
	v_fmac_f32_e32 v36, 0x3f317217, v35
	v_cmp_lt_f32_e64 s[22:23], |v35|, s82
	s_nop 1
	v_cndmask_b32_e64 v35, v35, v36, s[22:23]
	s_waitcnt vmcnt(6)
	v_lshlrev_b32_e32 v36, 16, v30
	v_and_b32_e32 v30, 0xffff0000, v30
	v_mul_f32_e32 v30, v141, v30
	v_fmac_f32_e32 v30, v143, v36
	v_lshlrev_b32_e32 v36, 16, v31
	v_fmac_f32_e32 v30, v117, v36
	v_and_b32_e32 v31, 0xffff0000, v31
	v_fmac_f32_e32 v30, v116, v31
	v_lshlrev_b32_e32 v31, 16, v32
	v_fmac_f32_e32 v30, v114, v31
	v_and_b32_e32 v31, 0xffff0000, v32
	v_fmac_f32_e32 v30, v113, v31
	v_lshlrev_b32_e32 v31, 16, v33
	v_fmac_f32_e32 v30, v112, v31
	v_and_b32_e32 v31, 0xffff0000, v33
	v_fmac_f32_e32 v30, v111, v31
	v_lshlrev_b32_e32 v31, 16, v26
	v_and_b32_e32 v26, 0xffff0000, v26
	v_mul_f32_e32 v26, v110, v26
	v_fmac_f32_e32 v26, v115, v31
	v_lshlrev_b32_e32 v31, 16, v27
	v_fmac_f32_e32 v26, v109, v31
	v_and_b32_e32 v27, 0xffff0000, v27
	v_fmac_f32_e32 v26, v108, v27
	v_lshlrev_b32_e32 v27, 16, v28
	v_fmac_f32_e32 v26, v107, v27
	v_and_b32_e32 v27, 0xffff0000, v28
	v_fmac_f32_e32 v26, v106, v27
	v_lshlrev_b32_e32 v27, 16, v29
	v_fmac_f32_e32 v26, v105, v27
	v_and_b32_e32 v27, 0xffff0000, v29
	v_add_f32_e32 v30, v142, v30
	v_fmac_f32_e32 v26, v104, v27
	v_add_f32_e32 v26, v30, v26
	v_mul_f32_e64 v27, |v26|, s77
	v_exp_f32_e32 v27, v27
	v_cndmask_b32_e64 v28, 0, v238, s[20:21]
	v_sub_f32_e32 v28, v35, v28
	v_sub_f32_e32 v28, v34, v28
	v_add_f32_e32 v27, 1.0, v27
	v_cmp_gt_f32_e64 s[20:21], s76, v27
	v_mul_f32_e32 v28, 0x3d800000, v28
	ds_write_b32 v53, v28 offset:6240
	v_cndmask_b32_e64 v29, 0, 32, s[20:21]
	v_ldexp_f32 v27, v27, v29
	v_log_f32_e32 v27, v27
	v_min_f32_e32 v26, 0, v26
	v_mul_f32_e32 v28, 0x3f317217, v27
	v_fma_f32 v28, v27, s81, -v28
	v_fmac_f32_e32 v28, 0x3377d1cf, v27
	v_fmac_f32_e32 v28, 0x3f317217, v27
	v_cmp_lt_f32_e64 s[22:23], |v27|, s82
	s_nop 1
	v_cndmask_b32_e64 v27, v27, v28, s[22:23]
	s_waitcnt vmcnt(4)
; __device__ __forceinline__ float bflo(unsigned w) { return __uint_as_float(w << 16); }
; __device__ __forceinline__ float bfhi(unsigned w) { return __uint_as_float(w & 0xffff0000u); }
; __device__ __forceinline__ void gla_gcum(LAS unsigned char* lds, const GlaArgs& A, int t0, int h, int tid) {
;     ...
;       for (int e = 0; e < 8; ++e) { const int i = i0 + 8 * e; const u32x4 a0 = al0[e], a1 = al1[e];
;           float x = ab;
;           x += bflo(a0.x) * au[0] + bfhi(a0.x) * au[1] + bflo(a0.y) * au[2] + bfhi(a0.y) * au[3] + bflo(a0.z) * au[4] + bfhi(a0.z) * au[5] + bflo(a0.w) * au[6] + bfhi(a0.w) * au[7];
;           x += bflo(a1.x) * au[8] + bfhi(a1.x) * au[9] + bflo(a1.y) * au[10] + bfhi(a1.y) * au[11] + bflo(a1.z) * au[12] + bfhi(a1.z) * au[13] + bflo(a1.w) * au[14] + bfhi(a1.w) * au[15];
;           const float ls = fminf(x, 0.f) - __logf(1.f + __expf(-fabsf(x)));
;           GC[i * 65 + d] = ls * (1.0f / 16.0f); } }
;     __syncthreads();
	v_lshlrev_b32_e32 v28, 16, v22
	v_and_b32_e32 v22, 0xffff0000, v22
	v_mul_f32_e32 v22, v141, v22
	v_fmac_f32_e32 v22, v143, v28
	v_lshlrev_b32_e32 v28, 16, v23
	v_fmac_f32_e32 v22, v117, v28
	v_and_b32_e32 v23, 0xffff0000, v23
	v_fmac_f32_e32 v22, v116, v23
	v_lshlrev_b32_e32 v23, 16, v24
	v_fmac_f32_e32 v22, v114, v23
	v_and_b32_e32 v23, 0xffff0000, v24
	v_fmac_f32_e32 v22, v113, v23
	v_lshlrev_b32_e32 v23, 16, v25
	v_fmac_f32_e32 v22, v112, v23
	v_and_b32_e32 v23, 0xffff0000, v25
	v_fmac_f32_e32 v22, v111, v23
	v_lshlrev_b32_e32 v23, 16, v18
	v_and_b32_e32 v18, 0xffff0000, v18
	v_mul_f32_e32 v18, v110, v18
	v_fmac_f32_e32 v18, v115, v23
	v_lshlrev_b32_e32 v23, 16, v19
	v_fmac_f32_e32 v18, v109, v23
	v_and_b32_e32 v19, 0xffff0000, v19
	v_fmac_f32_e32 v18, v108, v19
	v_lshlrev_b32_e32 v19, 16, v20
	v_fmac_f32_e32 v18, v107, v19
	v_and_b32_e32 v19, 0xffff0000, v20
	v_fmac_f32_e32 v18, v106, v19
	v_lshlrev_b32_e32 v19, 16, v21
	v_fmac_f32_e32 v18, v105, v19
	v_and_b32_e32 v19, 0xffff0000, v21
	v_add_f32_e32 v22, v142, v22
	v_fmac_f32_e32 v18, v104, v19
	v_add_f32_e32 v18, v22, v18
	v_mul_f32_e64 v19, |v18|, s77
	v_exp_f32_e32 v19, v19
	v_cndmask_b32_e64 v20, 0, v238, s[20:21]
	v_sub_f32_e32 v20, v27, v20
	v_sub_f32_e32 v20, v26, v20
	v_add_f32_e32 v19, 1.0, v19
	v_cmp_gt_f32_e64 s[20:21], s76, v19
	v_mul_f32_e32 v20, 0x3d800000, v20
	ds_write_b32 v53, v20 offset:8320
	v_cndmask_b32_e64 v21, 0, 32, s[20:21]
	v_ldexp_f32 v19, v19, v21
	v_log_f32_e32 v19, v19
	v_min_f32_e32 v18, 0, v18
	v_mul_f32_e32 v20, 0x3f317217, v19
	v_fma_f32 v20, v19, s81, -v20
	v_fmac_f32_e32 v20, 0x3377d1cf, v19
	v_fmac_f32_e32 v20, 0x3f317217, v19
	v_cmp_lt_f32_e64 s[22:23], |v19|, s82
	s_nop 1
	v_cndmask_b32_e64 v19, v19, v20, s[22:23]
	s_waitcnt vmcnt(2)
	v_lshlrev_b32_e32 v20, 16, v6
	v_and_b32_e32 v6, 0xffff0000, v6
	v_mul_f32_e32 v6, v141, v6
	v_fmac_f32_e32 v6, v143, v20
	v_lshlrev_b32_e32 v20, 16, v7
	v_fmac_f32_e32 v6, v117, v20
	v_and_b32_e32 v7, 0xffff0000, v7
	v_fmac_f32_e32 v6, v116, v7
	v_lshlrev_b32_e32 v7, 16, v8
	v_fmac_f32_e32 v6, v114, v7
	v_and_b32_e32 v7, 0xffff0000, v8
	v_fmac_f32_e32 v6, v113, v7
	v_lshlrev_b32_e32 v7, 16, v9
	v_fmac_f32_e32 v6, v112, v7
	v_and_b32_e32 v7, 0xffff0000, v9
	v_fmac_f32_e32 v6, v111, v7
	v_lshlrev_b32_e32 v7, 16, v2
	v_and_b32_e32 v2, 0xffff0000, v2
	v_mul_f32_e32 v2, v110, v2
	v_fmac_f32_e32 v2, v115, v7
	v_lshlrev_b32_e32 v7, 16, v3
	v_fmac_f32_e32 v2, v109, v7
	v_and_b32_e32 v3, 0xffff0000, v3
	v_fmac_f32_e32 v2, v108, v3
	v_lshlrev_b32_e32 v3, 16, v4
	v_fmac_f32_e32 v2, v107, v3
	v_and_b32_e32 v3, 0xffff0000, v4
	v_fmac_f32_e32 v2, v106, v3
	v_lshlrev_b32_e32 v3, 16, v5
	v_fmac_f32_e32 v2, v105, v3
	v_and_b32_e32 v3, 0xffff0000, v5
	v_add_f32_e32 v6, v142, v6
	v_fmac_f32_e32 v2, v104, v3
	v_add_f32_e32 v2, v6, v2
	v_mul_f32_e64 v3, |v2|, s77
	v_exp_f32_e32 v3, v3
	v_cndmask_b32_e64 v4, 0, v238, s[20:21]
	v_sub_f32_e32 v4, v19, v4
	v_sub_f32_e32 v4, v18, v4
	v_add_f32_e32 v3, 1.0, v3
	v_cmp_gt_f32_e64 s[20:21], s76, v3
	v_mul_f32_e32 v4, 0x3d800000, v4
	ds_write_b32 v53, v4 offset:10400
	v_cndmask_b32_e64 v5, 0, 32, s[20:21]
	v_ldexp_f32 v3, v3, v5
	v_log_f32_e32 v3, v3
	s_waitcnt vmcnt(0)
	v_and_b32_e32 v5, 0xffff0000, v14
	v_mul_f32_e32 v5, v141, v5
	v_and_b32_e32 v6, 0xffff0000, v10
	v_mul_f32_e32 v4, 0x3f317217, v3
	v_fma_f32 v4, v3, s81, -v4
	v_fmac_f32_e32 v4, 0x3377d1cf, v3
	v_fmac_f32_e32 v4, 0x3f317217, v3
	v_cmp_lt_f32_e64 s[22:23], |v3|, s82
	v_mul_f32_e32 v6, v110, v6
	v_min_f32_e32 v2, 0, v2
	v_cndmask_b32_e64 v3, v3, v4, s[22:23]
	v_lshlrev_b32_e32 v4, 16, v14
	v_fmac_f32_e32 v5, v143, v4
	v_lshlrev_b32_e32 v4, 16, v15
	v_fmac_f32_e32 v5, v117, v4
	v_and_b32_e32 v4, 0xffff0000, v15
	v_fmac_f32_e32 v5, v116, v4
	v_lshlrev_b32_e32 v4, 16, v16
	v_fmac_f32_e32 v5, v114, v4
	v_and_b32_e32 v4, 0xffff0000, v16
	v_fmac_f32_e32 v5, v113, v4
	v_lshlrev_b32_e32 v4, 16, v17
	v_fmac_f32_e32 v5, v112, v4
	v_and_b32_e32 v4, 0xffff0000, v17
	v_fmac_f32_e32 v5, v111, v4
	v_add_f32_e32 v4, v142, v5
	v_lshlrev_b32_e32 v5, 16, v10
	v_fmac_f32_e32 v6, v115, v5
	v_lshlrev_b32_e32 v5, 16, v11
	v_fmac_f32_e32 v6, v109, v5
	v_and_b32_e32 v5, 0xffff0000, v11
	v_fmac_f32_e32 v6, v108, v5
	v_lshlrev_b32_e32 v5, 16, v12
	v_fmac_f32_e32 v6, v107, v5
	v_and_b32_e32 v5, 0xffff0000, v12
	v_fmac_f32_e32 v6, v106, v5
	v_lshlrev_b32_e32 v5, 16, v13
	v_fmac_f32_e32 v6, v105, v5
	v_and_b32_e32 v5, 0xffff0000, v13
	v_fmac_f32_e32 v6, v104, v5
	v_add_f32_e32 v4, v4, v6
	v_mul_f32_e64 v5, |v4|, s77
	v_exp_f32_e32 v5, v5
	v_cndmask_b32_e64 v6, 0, v238, s[20:21]
	v_sub_f32_e32 v3, v3, v6
	v_sub_f32_e32 v2, v2, v3
	v_add_f32_e32 v3, 1.0, v5
	v_cmp_gt_f32_e64 s[20:21], s76, v3
	v_mul_f32_e32 v2, 0x3d800000, v2
	ds_write_b32 v53, v2 offset:12480
	v_cndmask_b32_e64 v5, 0, 32, s[20:21]
	v_ldexp_f32 v3, v3, v5
	v_log_f32_e32 v3, v3
	v_min_f32_e32 v2, 0, v4
	v_mul_f32_e32 v4, 0x3f317217, v3
	v_fma_f32 v4, v3, s81, -v4
	v_fmac_f32_e32 v4, 0x3377d1cf, v3
	v_fmac_f32_e32 v4, 0x3f317217, v3
	v_cmp_lt_f32_e64 s[22:23], |v3|, s82
	s_nop 1
	v_cndmask_b32_e64 v3, v3, v4, s[22:23]
	v_cndmask_b32_e64 v4, 0, v238, s[20:21]
	v_sub_f32_e32 v3, v3, v4
	v_sub_f32_e32 v2, v2, v3
	v_mul_f32_e32 v2, 0x3d800000, v2
	ds_write_b32 v53, v2 offset:14560
	s_waitcnt lgkmcnt(0)
	s_barrier
; __device__ __forceinline__ void gla_conv8(f32x4 (&out)[8], const bf16_t* Ug, const float* conv, int t0, int s0, int i0, int c0) {
;     f32x4 w[4];
; #pragma unroll
;     for (int j = 0; j < 4; ++j) w[j] = *(const f32x4*)(conv + j * 1024 + c0);
;     u32x2 raw[8][4];
; #pragma unroll
;     for (int e = 0; e < 8; ++e)
; #pragma unroll
;         for (int j = 0; j < 4; ++j) { const int i = i0 + 8 * e, ds = 3 - j; const bool ok = (s0 + i - ds) >= 0; raw[e][j] = *(const u32x2*)(Ug + (size_t)(ok ? t0 + i - ds : t0) * 1792 + c0); }
; __device__ __forceinline__ void gla_gcum(LAS unsigned char* lds, const GlaArgs& A, int t0, int h, int tid) {
;     ...
;     { const int lane = tid & 63, wave = tid >> 6;
; #pragma unroll
;       for (int dd = 0; dd < 8; ++dd) { const int d = wave * 8 + dd; float x = GC[lane * 65 + d];
; #pragma unroll
;           for (int o = 1; o < 64; o <<= 1) { const float y = __shfl_up(x, o); if (lane >= o) x += y; }
;           GC[lane * 65 + d] = x; } }
;     __syncthreads();
	ds_read2_b32 v[2:3], v132 offset1:1
	ds_read2_b32 v[4:5], v132 offset0:6 offset1:7
	ds_read2_b32 v[6:7], v132 offset0:2 offset1:3
	ds_read2_b32 v[12:13], v132 offset0:4 offset1:5
	s_waitcnt lgkmcnt(0)
	v_add_f32_dpp v2, v2, v2 row_shr:1 row_mask:0xf bank_mask:0xf
	v_add_f32_dpp v3, v3, v3 row_shr:1 row_mask:0xf bank_mask:0xf
	v_add_f32_dpp v6, v6, v6 row_shr:1 row_mask:0xf bank_mask:0xf
	v_add_f32_dpp v7, v7, v7 row_shr:1 row_mask:0xf bank_mask:0xf
	v_add_f32_dpp v12, v12, v12 row_shr:1 row_mask:0xf bank_mask:0xf
	v_add_f32_dpp v13, v13, v13 row_shr:1 row_mask:0xf bank_mask:0xf
	v_add_f32_dpp v4, v4, v4 row_shr:1 row_mask:0xf bank_mask:0xf
	v_add_f32_dpp v5, v5, v5 row_shr:1 row_mask:0xf bank_mask:0xf
	v_add_f32_dpp v2, v2, v2 row_shr:2 row_mask:0xf bank_mask:0xf
	v_add_f32_dpp v3, v3, v3 row_shr:2 row_mask:0xf bank_mask:0xf
	v_add_f32_dpp v6, v6, v6 row_shr:2 row_mask:0xf bank_mask:0xf
	v_add_f32_dpp v7, v7, v7 row_shr:2 row_mask:0xf bank_mask:0xf
	v_add_f32_dpp v12, v12, v12 row_shr:2 row_mask:0xf bank_mask:0xf
	v_add_f32_dpp v13, v13, v13 row_shr:2 row_mask:0xf bank_mask:0xf
	v_add_f32_dpp v4, v4, v4 row_shr:2 row_mask:0xf bank_mask:0xf
	v_add_f32_dpp v5, v5, v5 row_shr:2 row_mask:0xf bank_mask:0xf
	v_add_f32_dpp v2, v2, v2 row_shr:4 row_mask:0xf bank_mask:0xf
	v_add_f32_dpp v3, v3, v3 row_shr:4 row_mask:0xf bank_mask:0xf
	v_add_f32_dpp v6, v6, v6 row_shr:4 row_mask:0xf bank_mask:0xf
	v_add_f32_dpp v7, v7, v7 row_shr:4 row_mask:0xf bank_mask:0xf
	v_add_f32_dpp v12, v12, v12 row_shr:4 row_mask:0xf bank_mask:0xf
	v_add_f32_dpp v13, v13, v13 row_shr:4 row_mask:0xf bank_mask:0xf
	v_add_f32_dpp v4, v4, v4 row_shr:4 row_mask:0xf bank_mask:0xf
	v_add_f32_dpp v5, v5, v5 row_shr:4 row_mask:0xf bank_mask:0xf
	v_add_f32_dpp v2, v2, v2 row_shr:8 row_mask:0xf bank_mask:0xf
	v_add_f32_dpp v3, v3, v3 row_shr:8 row_mask:0xf bank_mask:0xf
	v_add_f32_dpp v6, v6, v6 row_shr:8 row_mask:0xf bank_mask:0xf
	v_add_f32_dpp v7, v7, v7 row_shr:8 row_mask:0xf bank_mask:0xf
	v_add_f32_dpp v12, v12, v12 row_shr:8 row_mask:0xf bank_mask:0xf
	v_add_f32_dpp v13, v13, v13 row_shr:8 row_mask:0xf bank_mask:0xf
	v_add_f32_dpp v4, v4, v4 row_shr:8 row_mask:0xf bank_mask:0xf
	v_add_f32_dpp v5, v5, v5 row_shr:8 row_mask:0xf bank_mask:0xf
	v_add_f32_dpp v2, v2, v2 row_bcast:15 row_mask:0xa bank_mask:0xf
	v_add_f32_dpp v3, v3, v3 row_bcast:15 row_mask:0xa bank_mask:0xf
	v_add_f32_dpp v6, v6, v6 row_bcast:15 row_mask:0xa bank_mask:0xf
	v_add_f32_dpp v7, v7, v7 row_bcast:15 row_mask:0xa bank_mask:0xf
	v_add_f32_dpp v12, v12, v12 row_bcast:15 row_mask:0xa bank_mask:0xf
	v_add_f32_dpp v13, v13, v13 row_bcast:15 row_mask:0xa bank_mask:0xf
	v_add_f32_dpp v4, v4, v4 row_bcast:15 row_mask:0xa bank_mask:0xf
	v_add_f32_dpp v5, v5, v5 row_bcast:15 row_mask:0xa bank_mask:0xf
	v_add_f32_dpp v2, v2, v2 row_bcast:31 row_mask:0xc bank_mask:0xf
	v_add_f32_dpp v3, v3, v3 row_bcast:31 row_mask:0xc bank_mask:0xf
	v_add_f32_dpp v6, v6, v6 row_bcast:31 row_mask:0xc bank_mask:0xf
	v_add_f32_dpp v7, v7, v7 row_bcast:31 row_mask:0xc bank_mask:0xf
	v_add_f32_dpp v12, v12, v12 row_bcast:31 row_mask:0xc bank_mask:0xf
	v_add_f32_dpp v13, v13, v13 row_bcast:31 row_mask:0xc bank_mask:0xf
	v_add_f32_dpp v4, v4, v4 row_bcast:31 row_mask:0xc bank_mask:0xf
	v_add_f32_dpp v5, v5, v5 row_bcast:31 row_mask:0xc bank_mask:0xf
	s_nop 1
	ds_write2_b32 v132, v2, v3 offset1:1
	ds_write2_b32 v132, v6, v7 offset0:2 offset1:3
	ds_write2_b32 v132, v12, v13 offset0:4 offset1:5
	ds_write2_b32 v132, v4, v5 offset0:6 offset1:7
	s_waitcnt lgkmcnt(0)
	s_barrier
	s_and_saveexec_b64 s[22:23], s[16:17]
	s_cbranch_execz .LBB0_197
	s_add_i32 s20, s30, s29
	v_add_u32_e32 v141, s29, v121
	v_add_u32_e32 v18, -3, v135
	v_mov_b32_e32 v150, s20
	v_cmp_gt_i32_e64 s[20:21], 3, v141
	v_add_u32_e32 v20, -2, v135
	v_add_u32_e32 v22, -1, v135
	v_cndmask_b32_e64 v18, v18, v150, s[20:21]
	v_mad_i64_i32 v[18:19], s[20:21], v18, s80, v[100:101]
	v_cmp_gt_i32_e64 s[20:21], 2, v141
	global_load_dwordx4 v[14:17], v[86:87], off
	global_load_dwordx4 v[10:13], v[94:95], off
	global_load_dwordx4 v[6:9], v[96:97], off
	global_load_dwordx4 v[2:5], v[98:99], off
	v_cndmask_b32_e64 v20, v20, v150, s[20:21]
	v_mad_i64_i32 v[20:21], s[20:21], v20, s80, v[100:101]
	v_cmp_gt_i32_e64 s[20:21], 1, v141
	s_nop 1
	v_cndmask_b32_e64 v22, v22, v150, s[20:21]
	v_mad_i64_i32 v[22:23], s[20:21], v22, s80, v[100:101]
	v_cmp_gt_i32_e64 s[20:21], 0, v141
	s_nop 1
	v_cndmask_b32_e64 v24, v135, v150, s[20:21]
	v_mad_i64_i32 v[24:25], s[20:21], v24, s80, v[100:101]
	global_load_dwordx2 v[142:143], v[18:19], off
	global_load_dwordx2 v[144:145], v[20:21], off
	global_load_dwordx2 v[146:147], v[22:23], off
	global_load_dwordx2 v[148:149], v[24:25], off
	v_add_u32_e32 v24, 8, v141
	v_add_u32_e32 v18, 5, v135
	v_cmp_gt_i32_e64 s[20:21], 3, v24
	v_add_u32_e32 v20, 6, v135
	v_add_u32_e32 v22, 7, v135
	v_cndmask_b32_e64 v18, v18, v150, s[20:21]
	v_mad_i64_i32 v[18:19], s[20:21], v18, s80, v[100:101]
	v_cmp_gt_i32_e64 s[20:21], 2, v24
	s_waitcnt vmcnt(3)
	v_and_b32_e32 v151, 0xffff0000, v142
	v_cndmask_b32_e64 v20, v20, v150, s[20:21]
	v_mad_i64_i32 v[20:21], s[20:21], v20, s80, v[100:101]
	v_cmp_gt_i32_e64 s[20:21], 1, v24
	s_waitcnt vmcnt(2)
; __device__ __forceinline__ float bflo(unsigned w) { return __uint_as_float(w << 16); }
; __device__ __forceinline__ float bfhi(unsigned w) { return __uint_as_float(w & 0xffff0000u); }
; __device__ __forceinline__ void gla_conv8(f32x4 (&out)[8], const bf16_t* Ug, const float* conv, int t0, int s0, int i0, int c0) {
;     f32x4 w[4];
; #pragma unroll
;     for (int j = 0; j < 4; ++j) w[j] = *(const f32x4*)(conv + j * 1024 + c0);
;     u32x2 raw[8][4];
; #pragma unroll
;     for (int e = 0; e < 8; ++e)
; #pragma unroll
;         for (int j = 0; j < 4; ++j) { const int i = i0 + 8 * e, ds = 3 - j; const bool ok = (s0 + i - ds) >= 0; raw[e][j] = *(const u32x2*)(Ug + (size_t)(ok ? t0 + i - ds : t0) * 1792 + c0); }
; #pragma unroll
;     for (int e = 0; e < 8; ++e) { const int i = i0 + 8 * e; f32x4 a = (f32x4){0.f, 0.f, 0.f, 0.f};
; #pragma unroll
;         for (int j = 0; j < 4; ++j) { const int ds = 3 - j; const float mk = ((s0 + i - ds) >= 0) ? 1.0f : 0.0f; const u32x2 r = raw[e][j];
;             a += (w[j] * mk) * (f32x4){bflo(r.x), bfhi(r.x), bflo(r.y), bfhi(r.y)}; }
	v_lshlrev_b32_e32 v152, 16, v144
	v_and_b32_e32 v153, 0xffff0000, v144
	v_cndmask_b32_e64 v22, v22, v150, s[20:21]
	v_mad_i64_i32 v[22:23], s[20:21], v22, s80, v[100:101]
	v_cmp_gt_i32_e64 s[20:21], 0, v24
	v_lshlrev_b32_e32 v144, 16, v145
	v_and_b32_e32 v145, 0xffff0000, v145
	v_cndmask_b32_e64 v24, v103, v150, s[20:21]
	v_mad_i64_i32 v[24:25], s[20:21], v24, s80, v[100:101]
	global_load_dwordx2 v[116:117], v[18:19], off
	global_load_dwordx2 v[114:115], v[20:21], off
	global_load_dwordx2 v[112:113], v[22:23], off
	global_load_dwordx2 v[110:111], v[24:25], off
	v_add_u32_e32 v24, 16, v141
	v_add_u32_e32 v18, 13, v135
	v_cmp_gt_i32_e64 s[20:21], 3, v24
	v_add_u32_e32 v20, 14, v135
	v_add_u32_e32 v22, 15, v135
	v_cndmask_b32_e64 v18, v18, v150, s[20:21]
	v_mad_i64_i32 v[18:19], s[20:21], v18, s80, v[100:101]
	v_cmp_gt_i32_e64 s[20:21], 2, v24
	s_nop 1
	v_cndmask_b32_e64 v20, v20, v150, s[20:21]
	v_mad_i64_i32 v[20:21], s[20:21], v20, s80, v[100:101]
	v_cmp_gt_i32_e64 s[20:21], 1, v24
	s_nop 1
	v_cndmask_b32_e64 v22, v22, v150, s[20:21]
	v_mad_i64_i32 v[22:23], s[20:21], v22, s80, v[100:101]
	v_cmp_gt_i32_e64 s[20:21], 0, v24
	s_nop 1
	v_cndmask_b32_e64 v24, v102, v150, s[20:21]
	v_mad_i64_i32 v[24:25], s[20:21], v24, s80, v[100:101]
	global_load_dwordx2 v[108:109], v[18:19], off
	global_load_dwordx2 v[106:107], v[20:21], off
	global_load_dwordx2 v[104:105], v[22:23], off
	global_load_dwordx2 v[102:103], v[24:25], off
	v_add_u32_e32 v24, 24, v141
	v_add_u32_e32 v18, 21, v135
	v_cmp_gt_i32_e64 s[20:21], 3, v24
	v_add_u32_e32 v20, 22, v135
	v_add_u32_e32 v22, 23, v135
	v_cndmask_b32_e64 v18, v18, v150, s[20:21]
	v_mad_i64_i32 v[18:19], s[20:21], v18, s80, v[100:101]
	v_cmp_gt_i32_e64 s[20:21], 2, v24
	s_nop 1
	v_cndmask_b32_e64 v20, v20, v150, s[20:21]
	v_mad_i64_i32 v[20:21], s[20:21], v20, s80, v[100:101]
	v_cmp_gt_i32_e64 s[20:21], 1, v24
	s_nop 1
	v_cndmask_b32_e64 v22, v22, v150, s[20:21]
	v_mad_i64_i32 v[22:23], s[20:21], v22, s80, v[100:101]
	v_cmp_gt_i32_e64 s[20:21], 0, v24
	s_nop 1
	v_cndmask_b32_e64 v24, v140, v150, s[20:21]
	v_mad_i64_i32 v[24:25], s[20:21], v24, s80, v[100:101]
	global_load_dwordx2 v[56:57], v[18:19], off
	global_load_dwordx2 v[54:55], v[20:21], off
	global_load_dwordx2 v[52:53], v[22:23], off
	global_load_dwordx2 v[50:51], v[24:25], off
	v_add_u32_e32 v24, 32, v141
	v_add_u32_e32 v18, 29, v135
	v_cmp_gt_i32_e64 s[20:21], 3, v24
	v_add_u32_e32 v20, 30, v135
	v_add_u32_e32 v22, 31, v135
	v_cndmask_b32_e64 v18, v18, v150, s[20:21]
	v_mad_i64_i32 v[18:19], s[20:21], v18, s80, v[100:101]
	v_cmp_gt_i32_e64 s[20:21], 2, v24
	s_nop 1
	v_cndmask_b32_e64 v20, v20, v150, s[20:21]
	v_mad_i64_i32 v[20:21], s[20:21], v20, s80, v[100:101]
	v_cmp_gt_i32_e64 s[20:21], 1, v24
	s_nop 1
	v_cndmask_b32_e64 v22, v22, v150, s[20:21]
	v_mad_i64_i32 v[22:23], s[20:21], v22, s80, v[100:101]
	v_cmp_gt_i32_e64 s[20:21], 0, v24
	s_nop 1
	v_cndmask_b32_e64 v24, v139, v150, s[20:21]
	v_mad_i64_i32 v[24:25], s[20:21], v24, s80, v[100:101]
	global_load_dwordx2 v[48:49], v[18:19], off
	global_load_dwordx2 v[46:47], v[20:21], off
	global_load_dwordx2 v[44:45], v[22:23], off
	global_load_dwordx2 v[42:43], v[24:25], off
	v_add_u32_e32 v24, 40, v141
	v_add_u32_e32 v18, 37, v135
	v_cmp_gt_i32_e64 s[20:21], 3, v24
	v_add_u32_e32 v20, 38, v135
	v_add_u32_e32 v22, 39, v135
	v_cndmask_b32_e64 v18, v18, v150, s[20:21]
	v_mad_i64_i32 v[18:19], s[20:21], v18, s80, v[100:101]
	v_cmp_gt_i32_e64 s[20:21], 2, v24
	s_nop 1
	v_cndmask_b32_e64 v20, v20, v150, s[20:21]
	v_mad_i64_i32 v[20:21], s[20:21], v20, s80, v[100:101]
	v_cmp_gt_i32_e64 s[20:21], 1, v24
	s_nop 1
	v_cndmask_b32_e64 v22, v22, v150, s[20:21]
	v_mad_i64_i32 v[22:23], s[20:21], v22, s80, v[100:101]
	v_cmp_gt_i32_e64 s[20:21], 0, v24
	s_nop 1
	v_cndmask_b32_e64 v24, v138, v150, s[20:21]
	v_mad_i64_i32 v[24:25], s[20:21], v24, s80, v[100:101]
	global_load_dwordx2 v[40:41], v[18:19], off
	global_load_dwordx2 v[38:39], v[20:21], off
	global_load_dwordx2 v[36:37], v[22:23], off
	global_load_dwordx2 v[34:35], v[24:25], off
	v_add_u32_e32 v24, 48, v141
	v_add_u32_e32 v18, 45, v135
	v_cmp_gt_i32_e64 s[20:21], 3, v24
	v_add_u32_e32 v20, 46, v135
	v_add_u32_e32 v22, 47, v135
	v_cndmask_b32_e64 v18, v18, v150, s[20:21]
	v_mad_i64_i32 v[18:19], s[20:21], v18, s80, v[100:101]
	v_cmp_gt_i32_e64 s[20:21], 2, v24
	s_nop 1
	v_cndmask_b32_e64 v20, v20, v150, s[20:21]
	v_mad_i64_i32 v[20:21], s[20:21], v20, s80, v[100:101]
	v_cmp_gt_i32_e64 s[20:21], 1, v24
	s_nop 1
	v_cndmask_b32_e64 v22, v22, v150, s[20:21]
	v_mad_i64_i32 v[22:23], s[20:21], v22, s80, v[100:101]
	v_cmp_gt_i32_e64 s[20:21], 0, v24
	s_nop 1
	v_cndmask_b32_e64 v24, v137, v150, s[20:21]
	v_mad_i64_i32 v[24:25], s[20:21], v24, s80, v[100:101]
	global_load_dwordx2 v[32:33], v[18:19], off
	global_load_dwordx2 v[30:31], v[20:21], off
	global_load_dwordx2 v[28:29], v[22:23], off
	global_load_dwordx2 v[26:27], v[24:25], off
	v_add_u32_e32 v22, 56, v141
	v_add_u32_e32 v18, 53, v135
	v_cmp_gt_i32_e64 s[20:21], 3, v22
	v_add_u32_e32 v20, 54, v135
	v_add_u32_e32 v23, 55, v135
	v_cndmask_b32_e64 v18, v18, v150, s[20:21]
	v_mad_i64_i32 v[18:19], s[20:21], v18, s80, v[100:101]
	v_cmp_gt_i32_e64 s[20:21], 2, v22
	s_nop 1
	v_cndmask_b32_e64 v20, v20, v150, s[20:21]
	v_mad_i64_i32 v[20:21], s[20:21], v20, s80, v[100:101]
	v_cmp_gt_i32_e64 s[20:21], 1, v22
	s_nop 1
	v_cndmask_b32_e64 v23, v23, v150, s[20:21]
	v_mad_i64_i32 v[138:139], s[20:21], v23, s80, v[100:101]
	v_cmp_gt_i32_e64 s[20:21], 0, v22
	s_nop 1
	v_cndmask_b32_e64 v22, v136, v150, s[20:21]
	v_mad_i64_i32 v[136:137], s[20:21], v22, s80, v[100:101]
	v_cmp_lt_i32_e64 s[20:21], 2, v141
	global_load_dwordx2 v[24:25], v[18:19], off
	global_load_dwordx2 v[22:23], v[20:21], off
	s_nop 0
	global_load_dwordx2 v[20:21], v[138:139], off
	global_load_dwordx2 v[18:19], v[136:137], off
	v_cndmask_b32_e64 v136, 0, 1.0, s[20:21]
	v_cmp_lt_i32_e64 s[20:21], 1, v141
	v_pk_mul_f32 v[138:139], v[136:137], v[16:17] op_sel_hi:[0,1]
	v_pk_mul_f32 v[136:137], v[136:137], v[14:15] op_sel_hi:[0,1]
	v_lshlrev_b32_e32 v150, 16, v142
	v_lshlrev_b32_e32 v142, 16, v143
	v_and_b32_e32 v143, 0xffff0000, v143
	v_cndmask_b32_e64 v140, 0, 1.0, s[20:21]
	v_cmp_lt_i32_e64 s[20:21], 0, v141
	v_pk_fma_f32 v[136:137], v[136:137], v[150:151], 0 op_sel_hi:[1,1,0]
	v_pk_fma_f32 v[138:139], v[138:139], v[142:143], 0 op_sel_hi:[1,1,0]
	v_pk_mul_f32 v[142:143], v[140:141], v[12:13] op_sel_hi:[0,1]
	v_pk_mul_f32 v[150:151], v[140:141], v[10:11] op_sel_hi:[0,1]
	v_cndmask_b32_e64 v140, 0, 1.0, s[20:21]
	v_cmp_lt_i32_e64 s[20:21], -1, v141
	v_pk_fma_f32 v[138:139], v[142:143], v[144:145], v[138:139]
	v_pk_fma_f32 v[136:137], v[150:151], v[152:153], v[136:137]
	v_pk_mul_f32 v[142:143], v[140:141], v[8:9] op_sel_hi:[0,1]
	v_pk_mul_f32 v[144:145], v[140:141], v[6:7] op_sel_hi:[0,1]
	s_waitcnt vmcnt(29)
; __device__ __forceinline__ float bflo(unsigned w) { return __uint_as_float(w << 16); }
; __device__ __forceinline__ float bfhi(unsigned w) { return __uint_as_float(w & 0xffff0000u); }
; __device__ __forceinline__ float sigmoidf_(float x) { return __builtin_amdgcn_rcpf(1.0f + __expf(-x)); }
; __device__ __forceinline__ void gla_conv8(f32x4 (&out)[8], const bf16_t* Ug, const float* conv, int t0, int s0, int i0, int c0) {
;     ...
;     for (int e = 0; e < 8; ++e) { const int i = i0 + 8 * e; f32x4 a = (f32x4){0.f, 0.f, 0.f, 0.f};
; #pragma unroll
;         for (int j = 0; j < 4; ++j) { const int ds = 3 - j; const float mk = ((s0 + i - ds) >= 0) ? 1.0f : 0.0f; const u32x2 r = raw[e][j];
;             a += (w[j] * mk) * (f32x4){bflo(r.x), bfhi(r.x), bflo(r.y), bfhi(r.y)}; }
; #pragma unroll
;         for (int q = 0; q < 4; ++q) a[q] = a[q] * sigmoidf_(a[q]);
;         out[e] = a; }
	v_lshlrev_b32_e32 v150, 16, v146
	v_and_b32_e32 v151, 0xffff0000, v146
	v_lshlrev_b32_e32 v146, 16, v147
	v_and_b32_e32 v147, 0xffff0000, v147
	v_cndmask_b32_e64 v140, 0, 1.0, s[20:21]
	v_pk_fma_f32 v[136:137], v[144:145], v[150:151], v[136:137]
	v_pk_fma_f32 v[138:139], v[142:143], v[146:147], v[138:139]
	v_pk_mul_f32 v[144:145], v[140:141], v[2:3] op_sel_hi:[0,1]
	s_waitcnt vmcnt(28)
	v_lshlrev_b32_e32 v146, 16, v148
	v_and_b32_e32 v147, 0xffff0000, v148
	v_pk_fma_f32 v[136:137], v[144:145], v[146:147], v[136:137]
	v_pk_mul_f32 v[142:143], v[140:141], v[4:5] op_sel_hi:[0,1]
	v_mul_f32_e32 v140, 0xbfb8aa3b, v137
	v_exp_f32_e32 v140, v140
	v_lshlrev_b32_e32 v148, 16, v149
	v_and_b32_e32 v149, 0xffff0000, v149
	v_pk_fma_f32 v[142:143], v[142:143], v[148:149], v[138:139]
	v_mul_f32_e32 v135, 0xbfb8aa3b, v136
	v_mul_f32_e32 v139, 0xbfb8aa3b, v142
	v_add_f32_e32 v138, 1.0, v140
	v_exp_f32_e32 v139, v139
	v_mul_f32_e32 v140, 0xbfb8aa3b, v143
	v_exp_f32_e32 v135, v135
	v_exp_f32_e32 v140, v140
	v_rcp_f32_e32 v144, v138
	v_add_f32_e32 v138, 1.0, v139
	v_add_f32_e32 v135, 1.0, v135
	v_rcp_f32_e32 v139, v138
	v_add_f32_e32 v138, 1.0, v140
	v_rcp_f32_e32 v135, v135
	v_rcp_f32_e32 v140, v138
	v_cmp_lt_i32_e64 s[20:21], -6, v141
	v_mul_f32_e32 v137, v137, v144
	v_mul_f32_e32 v138, v136, v135
	v_mul_f32_e32 v135, v143, v140
	v_cndmask_b32_e64 v140, 0, 1.0, s[20:21]
	v_cmp_lt_i32_e64 s[20:21], -7, v141
	v_mul_f32_e32 v136, v142, v139
	v_pk_mul_f32 v[142:143], v[140:141], v[16:17] op_sel_hi:[0,1]
	v_pk_mul_f32 v[144:145], v[140:141], v[14:15] op_sel_hi:[0,1]
	s_waitcnt vmcnt(27)
	v_lshlrev_b32_e32 v146, 16, v116
	v_and_b32_e32 v147, 0xffff0000, v116
	v_lshlrev_b32_e32 v116, 16, v117
	v_and_b32_e32 v117, 0xffff0000, v117
	v_cndmask_b32_e64 v140, 0, 1.0, s[20:21]
	v_cmp_lt_i32_e64 s[20:21], -8, v141
	v_pk_fma_f32 v[144:145], v[144:145], v[146:147], 0 op_sel_hi:[1,1,0]
	v_pk_fma_f32 v[116:117], v[142:143], v[116:117], 0 op_sel_hi:[1,1,0]
	v_pk_mul_f32 v[142:143], v[140:141], v[12:13] op_sel_hi:[0,1]
	v_pk_mul_f32 v[146:147], v[140:141], v[10:11] op_sel_hi:[0,1]
	s_waitcnt vmcnt(26)
	v_lshlrev_b32_e32 v148, 16, v114
	v_and_b32_e32 v149, 0xffff0000, v114
	v_lshlrev_b32_e32 v114, 16, v115
	v_and_b32_e32 v115, 0xffff0000, v115
	v_cndmask_b32_e64 v140, 0, 1.0, s[20:21]
	v_pk_fma_f32 v[114:115], v[142:143], v[114:115], v[116:117]
	v_pk_fma_f32 v[116:117], v[146:147], v[148:149], v[144:145]
	v_pk_mul_f32 v[142:143], v[140:141], v[8:9] op_sel_hi:[0,1]
	s_waitcnt vmcnt(25)
	v_lshlrev_b32_e32 v146, 16, v112
	v_and_b32_e32 v147, 0xffff0000, v112
	v_lshlrev_b32_e32 v112, 16, v113
	v_and_b32_e32 v113, 0xffff0000, v113
	v_cmp_lt_i32_e64 s[20:21], -9, v141
	v_pk_mul_f32 v[144:145], v[140:141], v[6:7] op_sel_hi:[0,1]
	v_pk_fma_f32 v[112:113], v[142:143], v[112:113], v[114:115]
	v_cndmask_b32_e64 v114, 0, 1.0, s[20:21]
	v_pk_fma_f32 v[116:117], v[144:145], v[146:147], v[116:117]
	v_pk_mul_f32 v[142:143], v[114:115], v[4:5] op_sel_hi:[0,1]
	v_pk_mul_f32 v[114:115], v[114:115], v[2:3] op_sel_hi:[0,1]
	s_waitcnt vmcnt(24)
	v_lshlrev_b32_e32 v144, 16, v110
	v_and_b32_e32 v145, 0xffff0000, v110
	v_pk_fma_f32 v[114:115], v[114:115], v[144:145], v[116:117]
	v_lshlrev_b32_e32 v110, 16, v111
	v_mul_f32_e32 v116, 0xbfb8aa3b, v114
	v_and_b32_e32 v111, 0xffff0000, v111
	v_exp_f32_e32 v139, v116
	v_mul_f32_e32 v116, 0xbfb8aa3b, v115
	v_exp_f32_e32 v140, v116
	v_pk_fma_f32 v[116:117], v[142:143], v[110:111], v[112:113]
	v_add_f32_e32 v110, 1.0, v139
	v_mul_f32_e32 v112, 0xbfb8aa3b, v116
	v_exp_f32_e32 v112, v112
	v_mul_f32_e32 v113, 0xbfb8aa3b, v117
	v_exp_f32_e32 v113, v113
	v_rcp_f32_e32 v110, v110
	v_add_f32_e32 v112, 1.0, v112
	v_add_f32_e32 v111, 1.0, v140
	v_rcp_f32_e32 v139, v112
	v_add_f32_e32 v112, 1.0, v113
	v_rcp_f32_e32 v111, v111
	v_rcp_f32_e32 v140, v112
	v_cmp_lt_i32_e64 s[20:21], -14, v141
	v_mul_f32_e32 v113, v114, v110
	v_mul_f32_e32 v112, v115, v111
	v_cndmask_b32_e64 v114, 0, 1.0, s[20:21]
	v_mul_f32_e32 v111, v116, v139
	v_mul_f32_e32 v110, v117, v140
	v_pk_mul_f32 v[116:117], v[114:115], v[16:17] op_sel_hi:[0,1]
	s_waitcnt vmcnt(23)
	v_lshlrev_b32_e32 v142, 16, v108
	v_and_b32_e32 v143, 0xffff0000, v108
	v_lshlrev_b32_e32 v108, 16, v109
	v_and_b32_e32 v109, 0xffff0000, v109
	v_cmp_lt_i32_e64 s[20:21], -15, v141
	v_pk_mul_f32 v[114:115], v[114:115], v[14:15] op_sel_hi:[0,1]
	v_pk_fma_f32 v[108:109], v[116:117], v[108:109], 0 op_sel_hi:[1,1,0]
	v_cndmask_b32_e64 v116, 0, 1.0, s[20:21]
	v_pk_fma_f32 v[114:115], v[114:115], v[142:143], 0 op_sel_hi:[1,1,0]
	v_pk_mul_f32 v[142:143], v[116:117], v[12:13] op_sel_hi:[0,1]
	v_pk_mul_f32 v[116:117], v[116:117], v[10:11] op_sel_hi:[0,1]
	s_waitcnt vmcnt(22)
	v_lshlrev_b32_e32 v144, 16, v106
	v_and_b32_e32 v145, 0xffff0000, v106
	v_lshlrev_b32_e32 v106, 16, v107
	v_and_b32_e32 v107, 0xffff0000, v107
	v_cmp_lt_i32_e64 s[20:21], -16, v141
	v_pk_fma_f32 v[106:107], v[142:143], v[106:107], v[108:109]
	v_pk_fma_f32 v[108:109], v[116:117], v[144:145], v[114:115]
	v_cndmask_b32_e64 v114, 0, 1.0, s[20:21]
	s_movk_i32 s20, 0xffef
	v_pk_mul_f32 v[116:117], v[114:115], v[8:9] op_sel_hi:[0,1]
	s_waitcnt vmcnt(21)
	v_lshlrev_b32_e32 v142, 16, v104
	v_and_b32_e32 v143, 0xffff0000, v104
	v_lshlrev_b32_e32 v104, 16, v105
	v_and_b32_e32 v105, 0xffff0000, v105
	v_cmp_lt_i32_e64 s[20:21], s20, v141
	v_pk_mul_f32 v[114:115], v[114:115], v[6:7] op_sel_hi:[0,1]
	v_pk_fma_f32 v[104:105], v[116:117], v[104:105], v[106:107]
	v_cndmask_b32_e64 v106, 0, 1.0, s[20:21]
	v_pk_fma_f32 v[108:109], v[114:115], v[142:143], v[108:109]
	v_pk_mul_f32 v[114:115], v[106:107], v[4:5] op_sel_hi:[0,1]
	v_pk_mul_f32 v[106:107], v[106:107], v[2:3] op_sel_hi:[0,1]
	s_waitcnt vmcnt(20)
; __device__ __forceinline__ float bflo(unsigned w) { return __uint_as_float(w << 16); }
; __device__ __forceinline__ float bfhi(unsigned w) { return __uint_as_float(w & 0xffff0000u); }
; __device__ __forceinline__ float sigmoidf_(float x) { return __builtin_amdgcn_rcpf(1.0f + __expf(-x)); }
; __device__ __forceinline__ void gla_conv8(f32x4 (&out)[8], const bf16_t* Ug, const float* conv, int t0, int s0, int i0, int c0) {
;     ...
;     for (int e = 0; e < 8; ++e) { const int i = i0 + 8 * e; f32x4 a = (f32x4){0.f, 0.f, 0.f, 0.f};
; #pragma unroll
;         for (int j = 0; j < 4; ++j) { const int ds = 3 - j; const float mk = ((s0 + i - ds) >= 0) ? 1.0f : 0.0f; const u32x2 r = raw[e][j];
;             a += (w[j] * mk) * (f32x4){bflo(r.x), bfhi(r.x), bflo(r.y), bfhi(r.y)}; }
; #pragma unroll
;         for (int q = 0; q < 4; ++q) a[q] = a[q] * sigmoidf_(a[q]);
;         out[e] = a; }
	v_lshlrev_b32_e32 v116, 16, v102
	v_and_b32_e32 v117, 0xffff0000, v102
	v_pk_fma_f32 v[106:107], v[106:107], v[116:117], v[108:109]
	v_lshlrev_b32_e32 v102, 16, v103
	v_mul_f32_e32 v108, 0xbfb8aa3b, v106
	v_and_b32_e32 v103, 0xffff0000, v103
	v_exp_f32_e32 v116, v108
	v_mul_f32_e32 v108, 0xbfb8aa3b, v107
	v_exp_f32_e32 v117, v108
	v_pk_fma_f32 v[108:109], v[114:115], v[102:103], v[104:105]
	v_add_f32_e32 v102, 1.0, v116
	v_mul_f32_e32 v104, 0xbfb8aa3b, v108
	v_exp_f32_e32 v104, v104
	v_mul_f32_e32 v105, 0xbfb8aa3b, v109
	v_exp_f32_e32 v105, v105
	v_rcp_f32_e32 v102, v102
	v_add_f32_e32 v104, 1.0, v104
	v_add_f32_e32 v103, 1.0, v117
	v_rcp_f32_e32 v114, v104
	v_add_f32_e32 v104, 1.0, v105
	v_rcp_f32_e32 v103, v103
	v_rcp_f32_e32 v115, v104
	s_movk_i32 s20, 0xffea
	v_cmp_lt_i32_e64 s[20:21], s20, v141
	v_mul_f32_e32 v105, v106, v102
	v_mul_f32_e32 v104, v107, v103
	v_cndmask_b32_e64 v106, 0, 1.0, s[20:21]
	s_movk_i32 s20, 0xffe9
	v_mul_f32_e32 v103, v108, v114
	v_mul_f32_e32 v102, v109, v115
	v_pk_mul_f32 v[108:109], v[106:107], v[16:17] op_sel_hi:[0,1]
	s_waitcnt vmcnt(19)
	v_lshlrev_b32_e32 v114, 16, v56
	v_and_b32_e32 v115, 0xffff0000, v56
	v_lshlrev_b32_e32 v56, 16, v57
	v_and_b32_e32 v57, 0xffff0000, v57
	v_cmp_lt_i32_e64 s[20:21], s20, v141
	v_pk_mul_f32 v[106:107], v[106:107], v[14:15] op_sel_hi:[0,1]
	v_pk_fma_f32 v[56:57], v[108:109], v[56:57], 0 op_sel_hi:[1,1,0]
	v_cndmask_b32_e64 v108, 0, 1.0, s[20:21]
	s_movk_i32 s20, 0xffe8
	v_pk_fma_f32 v[106:107], v[106:107], v[114:115], 0 op_sel_hi:[1,1,0]
	v_pk_mul_f32 v[114:115], v[108:109], v[12:13] op_sel_hi:[0,1]
	v_pk_mul_f32 v[108:109], v[108:109], v[10:11] op_sel_hi:[0,1]
	s_waitcnt vmcnt(18)
	v_lshlrev_b32_e32 v116, 16, v54
	v_and_b32_e32 v117, 0xffff0000, v54
	v_lshlrev_b32_e32 v54, 16, v55
	v_and_b32_e32 v55, 0xffff0000, v55
	v_cmp_lt_i32_e64 s[20:21], s20, v141
	v_pk_fma_f32 v[54:55], v[114:115], v[54:55], v[56:57]
	v_pk_fma_f32 v[56:57], v[108:109], v[116:117], v[106:107]
	v_cndmask_b32_e64 v106, 0, 1.0, s[20:21]
	s_movk_i32 s20, 0xffe7
	v_pk_mul_f32 v[108:109], v[106:107], v[8:9] op_sel_hi:[0,1]
	s_waitcnt vmcnt(17)
	v_lshlrev_b32_e32 v114, 16, v52
	v_and_b32_e32 v115, 0xffff0000, v52
	v_lshlrev_b32_e32 v52, 16, v53
	v_and_b32_e32 v53, 0xffff0000, v53
	v_cmp_lt_i32_e64 s[20:21], s20, v141
	v_pk_mul_f32 v[106:107], v[106:107], v[6:7] op_sel_hi:[0,1]
	v_pk_fma_f32 v[52:53], v[108:109], v[52:53], v[54:55]
	v_cndmask_b32_e64 v54, 0, 1.0, s[20:21]
	v_pk_fma_f32 v[56:57], v[106:107], v[114:115], v[56:57]
	v_pk_mul_f32 v[106:107], v[54:55], v[4:5] op_sel_hi:[0,1]
	v_pk_mul_f32 v[54:55], v[54:55], v[2:3] op_sel_hi:[0,1]
	s_waitcnt vmcnt(16)
	v_lshlrev_b32_e32 v108, 16, v50
	v_and_b32_e32 v109, 0xffff0000, v50
	v_pk_fma_f32 v[54:55], v[54:55], v[108:109], v[56:57]
	v_lshlrev_b32_e32 v50, 16, v51
	v_mul_f32_e32 v56, 0xbfb8aa3b, v54
	v_and_b32_e32 v51, 0xffff0000, v51
	v_exp_f32_e32 v108, v56
	v_mul_f32_e32 v56, 0xbfb8aa3b, v55
	v_exp_f32_e32 v109, v56
	v_pk_fma_f32 v[56:57], v[106:107], v[50:51], v[52:53]
	v_add_f32_e32 v50, 1.0, v108
	v_mul_f32_e32 v52, 0xbfb8aa3b, v56
	v_exp_f32_e32 v52, v52
	v_mul_f32_e32 v53, 0xbfb8aa3b, v57
	v_exp_f32_e32 v53, v53
	v_rcp_f32_e32 v50, v50
	v_add_f32_e32 v52, 1.0, v52
	v_add_f32_e32 v51, 1.0, v109
	v_rcp_f32_e32 v106, v52
	v_add_f32_e32 v52, 1.0, v53
	v_rcp_f32_e32 v51, v51
	v_rcp_f32_e32 v107, v52
	s_movk_i32 s20, 0xffe2
	v_cmp_lt_i32_e64 s[20:21], s20, v141
	v_mul_f32_e32 v53, v54, v50
	v_mul_f32_e32 v52, v55, v51
	v_cndmask_b32_e64 v54, 0, 1.0, s[20:21]
	v_mul_f32_e32 v51, v56, v106
	v_mul_f32_e32 v50, v57, v107
	v_pk_mul_f32 v[56:57], v[54:55], v[16:17] op_sel_hi:[0,1]
	s_waitcnt vmcnt(15)
	v_lshlrev_b32_e32 v106, 16, v48
	v_and_b32_e32 v107, 0xffff0000, v48
	v_lshlrev_b32_e32 v48, 16, v49
	v_and_b32_e32 v49, 0xffff0000, v49
	v_cmp_lt_i32_e64 s[20:21], s83, v141
	v_pk_mul_f32 v[54:55], v[54:55], v[14:15] op_sel_hi:[0,1]
	v_pk_fma_f32 v[48:49], v[56:57], v[48:49], 0 op_sel_hi:[1,1,0]
	v_cndmask_b32_e64 v56, 0, 1.0, s[20:21]
	s_movk_i32 s20, 0xffe0
	v_pk_fma_f32 v[54:55], v[54:55], v[106:107], 0 op_sel_hi:[1,1,0]
	v_pk_mul_f32 v[106:107], v[56:57], v[12:13] op_sel_hi:[0,1]
	v_pk_mul_f32 v[56:57], v[56:57], v[10:11] op_sel_hi:[0,1]
	s_waitcnt vmcnt(14)
	v_lshlrev_b32_e32 v108, 16, v46
	v_and_b32_e32 v109, 0xffff0000, v46
	v_lshlrev_b32_e32 v46, 16, v47
	v_and_b32_e32 v47, 0xffff0000, v47
	v_cmp_lt_i32_e64 s[20:21], s20, v141
	v_pk_fma_f32 v[46:47], v[106:107], v[46:47], v[48:49]
	v_pk_fma_f32 v[48:49], v[56:57], v[108:109], v[54:55]
	v_cndmask_b32_e64 v54, 0, 1.0, s[20:21]
	s_movk_i32 s20, 0xffdf
	v_pk_mul_f32 v[56:57], v[54:55], v[8:9] op_sel_hi:[0,1]
	s_waitcnt vmcnt(13)
	v_lshlrev_b32_e32 v106, 16, v44
	v_and_b32_e32 v107, 0xffff0000, v44
	v_lshlrev_b32_e32 v44, 16, v45
	v_and_b32_e32 v45, 0xffff0000, v45
	v_cmp_lt_i32_e64 s[20:21], s20, v141
	v_pk_mul_f32 v[54:55], v[54:55], v[6:7] op_sel_hi:[0,1]
	v_pk_fma_f32 v[44:45], v[56:57], v[44:45], v[46:47]
	v_cndmask_b32_e64 v46, 0, 1.0, s[20:21]
	v_pk_fma_f32 v[48:49], v[54:55], v[106:107], v[48:49]
	v_pk_mul_f32 v[54:55], v[46:47], v[4:5] op_sel_hi:[0,1]
	v_pk_mul_f32 v[46:47], v[46:47], v[2:3] op_sel_hi:[0,1]
	s_waitcnt vmcnt(12)
; __device__ __forceinline__ float bflo(unsigned w) { return __uint_as_float(w << 16); }
; __device__ __forceinline__ float bfhi(unsigned w) { return __uint_as_float(w & 0xffff0000u); }
; __device__ __forceinline__ float sigmoidf_(float x) { return __builtin_amdgcn_rcpf(1.0f + __expf(-x)); }
; __device__ __forceinline__ void gla_conv8(f32x4 (&out)[8], const bf16_t* Ug, const float* conv, int t0, int s0, int i0, int c0) {
;     ...
;     for (int e = 0; e < 8; ++e) { const int i = i0 + 8 * e; f32x4 a = (f32x4){0.f, 0.f, 0.f, 0.f};
; #pragma unroll
;         for (int j = 0; j < 4; ++j) { const int ds = 3 - j; const float mk = ((s0 + i - ds) >= 0) ? 1.0f : 0.0f; const u32x2 r = raw[e][j];
;             a += (w[j] * mk) * (f32x4){bflo(r.x), bfhi(r.x), bflo(r.y), bfhi(r.y)}; }
; #pragma unroll
;         for (int q = 0; q < 4; ++q) a[q] = a[q] * sigmoidf_(a[q]);
;         out[e] = a; }
	v_lshlrev_b32_e32 v56, 16, v42
	v_and_b32_e32 v57, 0xffff0000, v42
	v_pk_fma_f32 v[46:47], v[46:47], v[56:57], v[48:49]
	v_lshlrev_b32_e32 v42, 16, v43
	v_mul_f32_e32 v48, 0xbfb8aa3b, v46
	v_and_b32_e32 v43, 0xffff0000, v43
	v_exp_f32_e32 v56, v48
	v_mul_f32_e32 v48, 0xbfb8aa3b, v47
	v_exp_f32_e32 v57, v48
	v_pk_fma_f32 v[48:49], v[54:55], v[42:43], v[44:45]
	v_add_f32_e32 v42, 1.0, v56
	v_mul_f32_e32 v44, 0xbfb8aa3b, v48
	v_exp_f32_e32 v44, v44
	v_mul_f32_e32 v45, 0xbfb8aa3b, v49
	v_exp_f32_e32 v45, v45
	v_rcp_f32_e32 v42, v42
	v_add_f32_e32 v44, 1.0, v44
	v_add_f32_e32 v43, 1.0, v57
	v_rcp_f32_e32 v54, v44
	v_add_f32_e32 v44, 1.0, v45
	v_rcp_f32_e32 v43, v43
	v_rcp_f32_e32 v55, v44
	s_movk_i32 s20, 0xffda
	v_cmp_lt_i32_e64 s[20:21], s20, v141
	v_mul_f32_e32 v45, v46, v42
	v_mul_f32_e32 v44, v47, v43
	v_cndmask_b32_e64 v46, 0, 1.0, s[20:21]
	s_movk_i32 s20, 0xffd9
	v_mul_f32_e32 v43, v48, v54
	v_mul_f32_e32 v42, v49, v55
	v_pk_mul_f32 v[48:49], v[46:47], v[16:17] op_sel_hi:[0,1]
	s_waitcnt vmcnt(11)
	v_lshlrev_b32_e32 v54, 16, v40
	v_and_b32_e32 v55, 0xffff0000, v40
	v_lshlrev_b32_e32 v40, 16, v41
	v_and_b32_e32 v41, 0xffff0000, v41
	v_cmp_lt_i32_e64 s[20:21], s20, v141
	v_pk_mul_f32 v[46:47], v[46:47], v[14:15] op_sel_hi:[0,1]
	v_pk_fma_f32 v[40:41], v[48:49], v[40:41], 0 op_sel_hi:[1,1,0]
	v_cndmask_b32_e64 v48, 0, 1.0, s[20:21]
	s_movk_i32 s20, 0xffd8
	v_pk_fma_f32 v[46:47], v[46:47], v[54:55], 0 op_sel_hi:[1,1,0]
	v_pk_mul_f32 v[54:55], v[48:49], v[12:13] op_sel_hi:[0,1]
	v_pk_mul_f32 v[48:49], v[48:49], v[10:11] op_sel_hi:[0,1]
	s_waitcnt vmcnt(10)
	v_lshlrev_b32_e32 v56, 16, v38
	v_and_b32_e32 v57, 0xffff0000, v38
	v_lshlrev_b32_e32 v38, 16, v39
	v_and_b32_e32 v39, 0xffff0000, v39
	v_cmp_lt_i32_e64 s[20:21], s20, v141
	v_pk_fma_f32 v[38:39], v[54:55], v[38:39], v[40:41]
	v_pk_fma_f32 v[40:41], v[48:49], v[56:57], v[46:47]
	v_cndmask_b32_e64 v46, 0, 1.0, s[20:21]
	s_movk_i32 s20, 0xffd7
	v_pk_mul_f32 v[48:49], v[46:47], v[8:9] op_sel_hi:[0,1]
	s_waitcnt vmcnt(9)
	v_lshlrev_b32_e32 v54, 16, v36
	v_and_b32_e32 v55, 0xffff0000, v36
	v_lshlrev_b32_e32 v36, 16, v37
	v_and_b32_e32 v37, 0xffff0000, v37
	v_cmp_lt_i32_e64 s[20:21], s20, v141
	v_pk_mul_f32 v[46:47], v[46:47], v[6:7] op_sel_hi:[0,1]
	v_pk_fma_f32 v[36:37], v[48:49], v[36:37], v[38:39]
	v_cndmask_b32_e64 v38, 0, 1.0, s[20:21]
	v_pk_fma_f32 v[40:41], v[46:47], v[54:55], v[40:41]
	v_pk_mul_f32 v[46:47], v[38:39], v[4:5] op_sel_hi:[0,1]
	v_pk_mul_f32 v[38:39], v[38:39], v[2:3] op_sel_hi:[0,1]
	s_waitcnt vmcnt(8)
	v_lshlrev_b32_e32 v48, 16, v34
	v_and_b32_e32 v49, 0xffff0000, v34
	v_pk_fma_f32 v[38:39], v[38:39], v[48:49], v[40:41]
	v_lshlrev_b32_e32 v34, 16, v35
	v_mul_f32_e32 v40, 0xbfb8aa3b, v38
	v_and_b32_e32 v35, 0xffff0000, v35
	v_exp_f32_e32 v48, v40
	v_mul_f32_e32 v40, 0xbfb8aa3b, v39
	v_exp_f32_e32 v49, v40
	v_pk_fma_f32 v[40:41], v[46:47], v[34:35], v[36:37]
	v_add_f32_e32 v34, 1.0, v48
	v_mul_f32_e32 v36, 0xbfb8aa3b, v40
	v_exp_f32_e32 v36, v36
	v_mul_f32_e32 v37, 0xbfb8aa3b, v41
	v_exp_f32_e32 v37, v37
	v_rcp_f32_e32 v34, v34
	v_add_f32_e32 v36, 1.0, v36
	v_add_f32_e32 v35, 1.0, v49
	v_rcp_f32_e32 v46, v36
	v_add_f32_e32 v36, 1.0, v37
	v_rcp_f32_e32 v35, v35
	v_rcp_f32_e32 v47, v36
	s_movk_i32 s20, 0xffd2
	v_cmp_lt_i32_e64 s[20:21], s20, v141
	v_mul_f32_e32 v37, v38, v34
	v_mul_f32_e32 v36, v39, v35
	v_cndmask_b32_e64 v38, 0, 1.0, s[20:21]
	s_movk_i32 s20, 0xffd1
	v_mul_f32_e32 v35, v40, v46
	v_mul_f32_e32 v34, v41, v47
	v_pk_mul_f32 v[40:41], v[38:39], v[16:17] op_sel_hi:[0,1]
	s_waitcnt vmcnt(7)
	v_lshlrev_b32_e32 v46, 16, v32
	v_and_b32_e32 v47, 0xffff0000, v32
	v_lshlrev_b32_e32 v32, 16, v33
	v_and_b32_e32 v33, 0xffff0000, v33
	v_cmp_lt_i32_e64 s[20:21], s20, v141
	v_pk_mul_f32 v[38:39], v[38:39], v[14:15] op_sel_hi:[0,1]
	v_pk_fma_f32 v[32:33], v[40:41], v[32:33], 0 op_sel_hi:[1,1,0]
	v_cndmask_b32_e64 v40, 0, 1.0, s[20:21]
	s_movk_i32 s20, 0xffd0
	v_pk_fma_f32 v[38:39], v[38:39], v[46:47], 0 op_sel_hi:[1,1,0]
	v_pk_mul_f32 v[46:47], v[40:41], v[12:13] op_sel_hi:[0,1]
	v_pk_mul_f32 v[40:41], v[40:41], v[10:11] op_sel_hi:[0,1]
	s_waitcnt vmcnt(6)
	v_lshlrev_b32_e32 v48, 16, v30
	v_and_b32_e32 v49, 0xffff0000, v30
	v_lshlrev_b32_e32 v30, 16, v31
	v_and_b32_e32 v31, 0xffff0000, v31
	v_cmp_lt_i32_e64 s[20:21], s20, v141
	v_pk_fma_f32 v[30:31], v[46:47], v[30:31], v[32:33]
	v_pk_fma_f32 v[32:33], v[40:41], v[48:49], v[38:39]
	v_cndmask_b32_e64 v38, 0, 1.0, s[20:21]
	s_movk_i32 s20, 0xffcf
	v_pk_mul_f32 v[40:41], v[38:39], v[8:9] op_sel_hi:[0,1]
	s_waitcnt vmcnt(5)
	v_lshlrev_b32_e32 v46, 16, v28
	v_and_b32_e32 v47, 0xffff0000, v28
	v_lshlrev_b32_e32 v28, 16, v29
	v_and_b32_e32 v29, 0xffff0000, v29
	v_cmp_lt_i32_e64 s[20:21], s20, v141
	v_pk_mul_f32 v[38:39], v[38:39], v[6:7] op_sel_hi:[0,1]
	v_pk_fma_f32 v[28:29], v[40:41], v[28:29], v[30:31]
	v_cndmask_b32_e64 v30, 0, 1.0, s[20:21]
	v_pk_fma_f32 v[32:33], v[38:39], v[46:47], v[32:33]
	v_pk_mul_f32 v[38:39], v[30:31], v[4:5] op_sel_hi:[0,1]
	v_pk_mul_f32 v[30:31], v[30:31], v[2:3] op_sel_hi:[0,1]
	s_waitcnt vmcnt(4)
; __device__ __forceinline__ bf16_t f2bf(float x) { return (bf16_t)(cvt_pk_bf16(x, 0.f) & 0xffffu); }
; __device__ __forceinline__ float bflo(unsigned w) { return __uint_as_float(w << 16); }
; __device__ __forceinline__ float bfhi(unsigned w) { return __uint_as_float(w & 0xffff0000u); }
; __device__ __forceinline__ float sigmoidf_(float x) { return __builtin_amdgcn_rcpf(1.0f + __expf(-x)); }
; __device__ __forceinline__ void gla_conv8(f32x4 (&out)[8], const bf16_t* Ug, const float* conv, int t0, int s0, int i0, int c0) {
;     ...
;     for (int e = 0; e < 8; ++e) { const int i = i0 + 8 * e; f32x4 a = (f32x4){0.f, 0.f, 0.f, 0.f};
; #pragma unroll
;         for (int j = 0; j < 4; ++j) { const int ds = 3 - j; const float mk = ((s0 + i - ds) >= 0) ? 1.0f : 0.0f; const u32x2 r = raw[e][j];
;             a += (w[j] * mk) * (f32x4){bflo(r.x), bfhi(r.x), bflo(r.y), bfhi(r.y)}; }
; #pragma unroll
;         for (int q = 0; q < 4; ++q) a[q] = a[q] * sigmoidf_(a[q]);
;         out[e] = a; }
; __device__ __forceinline__ void gla_a_tile(LAS unsigned char* lds, const GlaArgs& A, int tile, int tid) {
;     ...
;           else { const int ev = cc - 128;
; #pragma unroll
;               for (int e = 0; e < 8; ++e) { const int i = i0 + 8 * e;
; #pragma unroll
;                   for (int q = 0; q < 4; ++q) VT[(ev + q) * 72 + i] = f2bf(o[e][q]); } } } }
	v_lshlrev_b32_e32 v40, 16, v26
	v_and_b32_e32 v41, 0xffff0000, v26
	v_pk_fma_f32 v[30:31], v[30:31], v[40:41], v[32:33]
	v_lshlrev_b32_e32 v26, 16, v27
	v_mul_f32_e32 v32, 0xbfb8aa3b, v30
	v_exp_f32_e32 v40, v32
	v_mul_f32_e32 v32, 0xbfb8aa3b, v31
	v_and_b32_e32 v27, 0xffff0000, v27
	v_exp_f32_e32 v41, v32
	v_pk_fma_f32 v[32:33], v[38:39], v[26:27], v[28:29]
	v_add_f32_e32 v26, 1.0, v40
	v_mul_f32_e32 v28, 0xbfb8aa3b, v32
	v_exp_f32_e32 v28, v28
	v_mul_f32_e32 v29, 0xbfb8aa3b, v33
	v_rcp_f32_e32 v26, v26
	v_add_f32_e32 v27, 1.0, v41
	v_exp_f32_e32 v29, v29
	v_rcp_f32_e32 v27, v27
	s_movk_i32 s20, 0xffca
	v_add_f32_e32 v28, 1.0, v28
	v_cmp_lt_i32_e64 s[20:21], s20, v141
	v_rcp_f32_e32 v38, v28
	v_add_f32_e32 v28, 1.0, v29
	v_mul_f32_e32 v29, v30, v26
	v_cndmask_b32_e64 v30, 0, 1.0, s[20:21]
	s_movk_i32 s20, 0xffc9
	v_rcp_f32_e32 v39, v28
	v_mul_f32_e32 v28, v31, v27
	v_pk_mul_f32 v[16:17], v[30:31], v[16:17] op_sel_hi:[0,1]
	v_pk_mul_f32 v[14:15], v[30:31], v[14:15] op_sel_hi:[0,1]
	s_waitcnt vmcnt(3)
	v_lshlrev_b32_e32 v30, 16, v24
	v_and_b32_e32 v31, 0xffff0000, v24
	v_lshlrev_b32_e32 v24, 16, v25
	v_and_b32_e32 v25, 0xffff0000, v25
	v_cmp_lt_i32_e64 s[20:21], s20, v141
	v_pk_fma_f32 v[16:17], v[16:17], v[24:25], 0 op_sel_hi:[1,1,0]
	v_pk_fma_f32 v[14:15], v[14:15], v[30:31], 0 op_sel_hi:[1,1,0]
	v_cndmask_b32_e64 v24, 0, 1.0, s[20:21]
	s_movk_i32 s20, 0xffc8
	v_pk_mul_f32 v[12:13], v[24:25], v[12:13] op_sel_hi:[0,1]
	v_pk_mul_f32 v[10:11], v[24:25], v[10:11] op_sel_hi:[0,1]
	s_waitcnt vmcnt(2)
	v_lshlrev_b32_e32 v24, 16, v22
	v_and_b32_e32 v25, 0xffff0000, v22
	v_cmp_lt_i32_e64 s[20:21], s20, v141
	v_pk_fma_f32 v[10:11], v[10:11], v[24:25], v[14:15]
	v_lshlrev_b32_e32 v22, 16, v23
	v_cndmask_b32_e64 v14, 0, 1.0, s[20:21]
	s_movk_i32 s20, 0xffc7
	v_and_b32_e32 v23, 0xffff0000, v23
	v_pk_mul_f32 v[8:9], v[14:15], v[8:9] op_sel_hi:[0,1]
	v_pk_mul_f32 v[6:7], v[14:15], v[6:7] op_sel_hi:[0,1]
	s_waitcnt vmcnt(1)
	v_lshlrev_b32_e32 v14, 16, v20
	v_and_b32_e32 v15, 0xffff0000, v20
	v_cmp_lt_i32_e64 s[20:21], s20, v141
	v_pk_fma_f32 v[12:13], v[12:13], v[22:23], v[16:17]
	v_lshlrev_b32_e32 v16, 16, v21
	v_and_b32_e32 v17, 0xffff0000, v21
	v_pk_fma_f32 v[6:7], v[6:7], v[14:15], v[10:11]
	v_cndmask_b32_e64 v10, 0, 1.0, s[20:21]
	v_pk_fma_f32 v[8:9], v[8:9], v[16:17], v[12:13]
	v_pk_mul_f32 v[4:5], v[10:11], v[4:5] op_sel_hi:[0,1]
	s_waitcnt vmcnt(0)
	v_lshlrev_b32_e32 v12, 16, v19
	v_and_b32_e32 v13, 0xffff0000, v19
	v_pk_mul_f32 v[2:3], v[10:11], v[2:3] op_sel_hi:[0,1]
	v_lshlrev_b32_e32 v10, 16, v18
	v_and_b32_e32 v11, 0xffff0000, v18
	v_pk_fma_f32 v[4:5], v[4:5], v[12:13], v[8:9]
	v_pk_fma_f32 v[2:3], v[2:3], v[10:11], v[6:7]
	v_mul_f32_e32 v8, 0xbfb8aa3b, v4
	v_mul_f32_e32 v6, 0xbfb8aa3b, v2
	v_mul_f32_e32 v7, 0xbfb8aa3b, v3
	v_exp_f32_e32 v8, v8
	v_mul_f32_e32 v9, 0xbfb8aa3b, v5
	v_exp_f32_e32 v6, v6
	v_exp_f32_e32 v7, v7
	v_exp_f32_e32 v9, v9
	v_add_f32_e32 v8, 1.0, v8
	v_add_f32_e32 v6, 1.0, v6
	v_add_f32_e32 v7, 1.0, v7
	v_rcp_f32_e32 v10, v8
	v_add_f32_e32 v8, 1.0, v9
	v_rcp_f32_e32 v6, v6
	v_rcp_f32_e32 v7, v7
	v_rcp_f32_e32 v11, v8
	v_mul_f32_e32 v27, v32, v38
	v_mul_f32_e32 v26, v33, v39
	v_mul_f32_e32 v9, v2, v6
	v_mul_f32_e32 v8, v3, v7
	v_mul_f32_e32 v7, v4, v10
	v_mul_f32_e32 v6, v5, v11
	s_and_saveexec_b64 s[20:21], s[14:15]
	s_xor_b64 s[20:21], exec, s[20:21]
	s_cbranch_execz .LBB0_195
	v_cvt_pk_bf16_f32 v2, v138, s0
	ds_write_b16 v0, v2 offset:35072
	v_cvt_pk_bf16_f32 v2, v137, s0
	ds_write_b16 v0, v2 offset:35216
	v_cvt_pk_bf16_f32 v2, v136, s0
	ds_write_b16 v0, v2 offset:35360
	v_cvt_pk_bf16_f32 v2, v135, s0
	ds_write_b16 v0, v2 offset:35504
	v_cvt_pk_bf16_f32 v2, v113, s0
	ds_write_b16 v0, v2 offset:35088
	v_cvt_pk_bf16_f32 v2, v112, s0
	ds_write_b16 v0, v2 offset:35232
	v_cvt_pk_bf16_f32 v2, v111, s0
	ds_write_b16 v0, v2 offset:35376
	v_cvt_pk_bf16_f32 v2, v110, s0
	ds_write_b16 v0, v2 offset:35520
	v_cvt_pk_bf16_f32 v2, v105, s0
	ds_write_b16 v0, v2 offset:35104
	v_cvt_pk_bf16_f32 v2, v104, s0
	ds_write_b16 v0, v2 offset:35248
	v_cvt_pk_bf16_f32 v2, v103, s0
	ds_write_b16 v0, v2 offset:35392
	v_cvt_pk_bf16_f32 v2, v102, s0
	ds_write_b16 v0, v2 offset:35536
	v_cvt_pk_bf16_f32 v2, v53, s0
	ds_write_b16 v0, v2 offset:35120
	v_cvt_pk_bf16_f32 v2, v52, s0
	ds_write_b16 v0, v2 offset:35264
	v_cvt_pk_bf16_f32 v2, v51, s0
	ds_write_b16 v0, v2 offset:35408
	v_cvt_pk_bf16_f32 v2, v50, s0
	ds_write_b16 v0, v2 offset:35552
	v_cvt_pk_bf16_f32 v2, v45, s0
	ds_write_b16 v0, v2 offset:35136
	v_cvt_pk_bf16_f32 v2, v44, s0
	ds_write_b16 v0, v2 offset:35280
	v_cvt_pk_bf16_f32 v2, v43, s0
	ds_write_b16 v0, v2 offset:35424
	v_cvt_pk_bf16_f32 v2, v42, s0
	ds_write_b16 v0, v2 offset:35568
	v_cvt_pk_bf16_f32 v2, v37, s0
	ds_write_b16 v0, v2 offset:35152
	v_cvt_pk_bf16_f32 v2, v36, s0
	ds_write_b16 v0, v2 offset:35296
	v_cvt_pk_bf16_f32 v2, v35, s0
	ds_write_b16 v0, v2 offset:35440
	v_cvt_pk_bf16_f32 v2, v34, s0
	ds_write_b16 v0, v2 offset:35584
	v_cvt_pk_bf16_f32 v2, v29, s0
	ds_write_b16 v0, v2 offset:35168
	v_cvt_pk_bf16_f32 v2, v28, s0
	ds_write_b16 v0, v2 offset:35312
	v_cvt_pk_bf16_f32 v2, v27, s0
	ds_write_b16 v0, v2 offset:35456
	v_cvt_pk_bf16_f32 v2, v26, s0
	ds_write_b16 v0, v2 offset:35600
	v_cvt_pk_bf16_f32 v2, v9, s0
	ds_write_b16 v0, v2 offset:35184
	v_cvt_pk_bf16_f32 v2, v8, s0
	ds_write_b16 v0, v2 offset:35328
	v_cvt_pk_bf16_f32 v2, v7, s0
	ds_write_b16 v0, v2 offset:35472
	v_cvt_pk_bf16_f32 v2, v6, s0
	ds_write_b16 v0, v2 offset:35616

; __device__ __forceinline__ float bflo(unsigned w) { return __uint_as_float(w << 16); }
; __device__ __forceinline__ float bfhi(unsigned w) { return __uint_as_float(w & 0xffff0000u); }
; __device__ __forceinline__ void gla_gcum(LAS unsigned char* lds, const GlaArgs& A, int t0, int h, int tid) {
;     ...
;     { const int d = tid & 63, i0 = tid >> 6; float au[16]; const float ab = A.abias[h * 64 + d];
; #pragma unroll
;       for (int j = 0; j < 16; ++j) au[j] = A.aup[j * 256 + h * 64 + d];
;       u32x4 al0[8], al1[8];
; #pragma unroll
;       for (int e = 0; e < 8; ++e) { const u32x4* ap = (const u32x4*)(A.Ug + (size_t)(t0 + i0 + 8 * e) * 1792 + 1024); al0[e] = ap[0]; al1[e] = ap[1]; }
; #pragma unroll
;       for (int e = 0; e < 8; ++e) { const int i = i0 + 8 * e; const u32x4 a0 = al0[e], a1 = al1[e];
;           float x = ab;
;           x += bflo(a0.x) * au[0] + bfhi(a0.x) * au[1] + bflo(a0.y) * au[2] + bfhi(a0.y) * au[3] + bflo(a0.z) * au[4] + bfhi(a0.z) * au[5] + bflo(a0.w) * au[6] + bfhi(a0.w) * au[7];
;           x += bflo(a1.x) * au[8] + bfhi(a1.x) * au[9] + bflo(a1.y) * au[10] + bfhi(a1.y) * au[11] + bflo(a1.z) * au[12] + bfhi(a1.z) * au[13] + bflo(a1.w) * au[14] + bfhi(a1.w) * au[15];
;           const float ls = fminf(x, 0.f) - __logf(1.f + __expf(-fabsf(x)));
;           GC[i * 65 + d] = ls * (1.0f / 16.0f); } }
.LBB0_310:
	v_add_u32_e32 v155, s62, v144
	v_mov_b64_e32 v[2:3], s[54:55]
	v_mad_i64_i32 v[4:5], s[38:39], v155, s80, v[2:3]
	global_load_dwordx4 v[10:13], v[4:5], off offset:2048
	global_load_dwordx4 v[14:17], v[4:5], off offset:2064
	global_load_dword v161, v[60:61], off offset:1024
	global_load_dword v160, v[60:61], off offset:2048
	global_load_dword v159, v[60:61], off offset:3072
	global_load_dword v122, v[62:63], off
	global_load_dword v121, v[64:65], off
	global_load_dword v120, v[66:67], off
	global_load_dword v119, v[68:69], off
	global_load_dword v163, v[60:61], off
	global_load_dword v118, v[72:73], off
	global_load_dword v117, v[74:75], off
	global_load_dword v116, v[76:77], off
	global_load_dword v115, v[78:79], off
	global_load_dword v114, v[80:81], off
	global_load_dword v113, v[82:83], off
	global_load_dword v112, v[84:85], off
	global_load_dword v123, v[70:71], off
	global_load_dword v162, v[58:59], off
	v_add_u32_e32 v111, 8, v155
	v_mad_i64_i32 v[4:5], s[38:39], v111, s80, v[2:3]
	global_load_dwordx4 v[50:53], v[4:5], off offset:2048
	global_load_dwordx4 v[54:57], v[4:5], off offset:2064
	v_add_u32_e32 v110, 16, v155
	v_add_u32_e32 v109, 24, v155
	v_add_u32_e32 v108, 32, v155
	v_add_u32_e32 v158, 40, v155
	v_add_u32_e32 v157, 48, v155
	v_add_u32_e32 v156, 56, v155
	v_mad_i64_i32 v[6:7], s[38:39], v110, s80, v[2:3]
	v_mad_i64_i32 v[8:9], s[38:39], v109, s80, v[2:3]
	v_mad_i64_i32 v[18:19], s[38:39], v108, s80, v[2:3]
	v_mad_i64_i32 v[22:23], s[38:39], v158, s80, v[2:3]
	v_mad_i64_i32 v[164:165], s[38:39], v157, s80, v[2:3]
	v_mad_i64_i32 v[166:167], s[38:39], v156, s80, v[2:3]
	global_load_dwordx4 v[42:45], v[6:7], off offset:2064
	global_load_dwordx4 v[46:49], v[6:7], off offset:2048
	global_load_dwordx4 v[34:37], v[8:9], off offset:2064
	global_load_dwordx4 v[38:41], v[8:9], off offset:2048
	global_load_dwordx4 v[26:29], v[18:19], off offset:2064
	global_load_dwordx4 v[30:33], v[18:19], off offset:2048
	s_nop 0
	global_load_dwordx4 v[18:21], v[22:23], off offset:2064
	s_nop 0
	global_load_dwordx4 v[22:25], v[22:23], off offset:2048
	s_nop 0
	global_load_dwordx4 v[2:5], v[164:165], off offset:2064
	global_load_dwordx4 v[6:9], v[164:165], off offset:2048
	s_movk_i32 s36, 0xffef
	s_waitcnt vmcnt(30)
	v_lshlrev_b32_e32 v164, 16, v10
	v_and_b32_e32 v10, 0xffff0000, v10
	s_waitcnt vmcnt(29)
	v_lshlrev_b32_e32 v170, 16, v14
	v_and_b32_e32 v14, 0xffff0000, v14
	s_waitcnt vmcnt(28)
	v_mul_f32_e32 v10, v161, v10
	v_lshlrev_b32_e32 v165, 16, v11
	v_and_b32_e32 v11, 0xffff0000, v11
	v_lshlrev_b32_e32 v171, 16, v15
	v_lshlrev_b32_e32 v168, 16, v12
	s_waitcnt vmcnt(21)
	v_fmac_f32_e32 v10, v163, v164
	s_waitcnt vmcnt(20)
	v_mul_f32_e32 v14, v118, v14
	v_fmac_f32_e32 v10, v160, v165
	v_and_b32_e32 v15, 0xffff0000, v15
	v_fmac_f32_e32 v10, v159, v11
	v_and_b32_e32 v12, 0xffff0000, v12
	v_lshlrev_b32_e32 v172, 16, v16
	v_fmac_f32_e32 v10, v122, v168
	s_waitcnt vmcnt(13)
	v_fmac_f32_e32 v14, v123, v170
	v_fmac_f32_e32 v14, v117, v171
	v_fmac_f32_e32 v14, v116, v15
	v_lshlrev_b32_e32 v169, 16, v13
	v_and_b32_e32 v16, 0xffff0000, v16
	v_fmac_f32_e32 v14, v115, v172
	v_fmac_f32_e32 v10, v121, v12
	v_and_b32_e32 v13, 0xffff0000, v13
	v_lshlrev_b32_e32 v173, 16, v17
	v_fmac_f32_e32 v14, v114, v16
	v_fmac_f32_e32 v10, v120, v169
	v_and_b32_e32 v17, 0xffff0000, v17
	v_fmac_f32_e32 v14, v113, v173
	v_fmac_f32_e32 v10, v119, v13
	v_fmac_f32_e32 v14, v112, v17
	s_waitcnt vmcnt(12)
	v_add_f32_e32 v10, v162, v10
	v_add_f32_e32 v164, v10, v14
	v_mul_f32_e64 v10, |v164|, s77
	v_exp_f32_e32 v165, v10
	global_load_dwordx4 v[10:13], v[166:167], off offset:2064
	global_load_dwordx4 v[14:17], v[166:167], off offset:2048
	s_waitcnt vmcnt(13)
	v_lshlrev_b32_e32 v166, 16, v50
	v_and_b32_e32 v50, 0xffff0000, v50
	v_mul_f32_e32 v50, v161, v50
	v_fmac_f32_e32 v50, v163, v166
	v_lshlrev_b32_e32 v166, 16, v51
	v_fmac_f32_e32 v50, v160, v166
	v_and_b32_e32 v51, 0xffff0000, v51
	v_fmac_f32_e32 v50, v159, v51
	v_lshlrev_b32_e32 v51, 16, v52
	v_fmac_f32_e32 v50, v122, v51
	v_and_b32_e32 v51, 0xffff0000, v52
	v_fmac_f32_e32 v50, v121, v51
	v_lshlrev_b32_e32 v51, 16, v53
	v_fmac_f32_e32 v50, v120, v51
	v_and_b32_e32 v51, 0xffff0000, v53
	s_waitcnt vmcnt(12)
	v_and_b32_e32 v52, 0xffff0000, v54
	v_fmac_f32_e32 v50, v119, v51
	v_lshlrev_b32_e32 v51, 16, v54
	v_mul_f32_e32 v52, v118, v52
	v_fmac_f32_e32 v52, v123, v51
	v_lshlrev_b32_e32 v51, 16, v55
	v_fmac_f32_e32 v52, v117, v51
	v_and_b32_e32 v51, 0xffff0000, v55
	v_add_f32_e32 v165, 1.0, v165
	v_fmac_f32_e32 v52, v116, v51
	v_lshlrev_b32_e32 v51, 16, v56
	v_cmp_gt_f32_e32 vcc, s76, v165
	v_fmac_f32_e32 v52, v115, v51
	v_and_b32_e32 v51, 0xffff0000, v56
	v_cndmask_b32_e64 v167, 0, 32, vcc
	v_fmac_f32_e32 v52, v114, v51
	v_lshlrev_b32_e32 v51, 16, v57
	v_ldexp_f32 v165, v165, v167
	v_fmac_f32_e32 v52, v113, v51
	v_and_b32_e32 v51, 0xffff0000, v57
	v_log_f32_e32 v165, v165
	v_add_f32_e32 v50, v162, v50
	v_fmac_f32_e32 v52, v112, v51
	v_add_f32_e32 v50, v50, v52
	v_mul_f32_e64 v51, |v50|, s77
	v_exp_f32_e32 v51, v51
	v_mul_f32_e32 v168, 0x3f317217, v165
	v_fma_f32 v168, v165, s81, -v168
	v_fmac_f32_e32 v168, 0x3377d1cf, v165
	v_cndmask_b32_e32 v167, 0, v238, vcc
	v_fmac_f32_e32 v168, 0x3f317217, v165
	v_cmp_lt_f32_e64 vcc, |v165|, s82
	v_add_f32_e32 v51, 1.0, v51
	v_min_f32_e32 v164, 0, v164
	v_cndmask_b32_e32 v165, v165, v168, vcc
	v_cmp_gt_f32_e32 vcc, s76, v51
	v_sub_f32_e32 v52, v165, v167
	v_sub_f32_e32 v52, v164, v52
	v_cndmask_b32_e64 v53, 0, 32, vcc
	v_ldexp_f32 v51, v51, v53
	v_log_f32_e32 v51, v51
	v_mul_f32_e32 v52, 0x3d800000, v52
	v_add_u32_e32 v53, v132, v133
	ds_write_b32 v53, v52
	v_mul_f32_e32 v52, 0x3f317217, v51
	v_fma_f32 v52, v51, s81, -v52
	v_fmac_f32_e32 v52, 0x3377d1cf, v51
	v_fmac_f32_e32 v52, 0x3f317217, v51
	v_cmp_lt_f32_e64 s[38:39], |v51|, s82
	v_min_f32_e32 v50, 0, v50
	s_nop 0
	v_cndmask_b32_e64 v51, v51, v52, s[38:39]
	s_waitcnt vmcnt(10)
; __device__ __forceinline__ float bflo(unsigned w) { return __uint_as_float(w << 16); }
; __device__ __forceinline__ float bfhi(unsigned w) { return __uint_as_float(w & 0xffff0000u); }
; __device__ __forceinline__ void gla_gcum(LAS unsigned char* lds, const GlaArgs& A, int t0, int h, int tid) {
;     ...
;       for (int e = 0; e < 8; ++e) { const int i = i0 + 8 * e; const u32x4 a0 = al0[e], a1 = al1[e];
;           float x = ab;
;           x += bflo(a0.x) * au[0] + bfhi(a0.x) * au[1] + bflo(a0.y) * au[2] + bfhi(a0.y) * au[3] + bflo(a0.z) * au[4] + bfhi(a0.z) * au[5] + bflo(a0.w) * au[6] + bfhi(a0.w) * au[7];
;           x += bflo(a1.x) * au[8] + bfhi(a1.x) * au[9] + bflo(a1.y) * au[10] + bfhi(a1.y) * au[11] + bflo(a1.z) * au[12] + bfhi(a1.z) * au[13] + bflo(a1.w) * au[14] + bfhi(a1.w) * au[15];
;           const float ls = fminf(x, 0.f) - __logf(1.f + __expf(-fabsf(x)));
;           GC[i * 65 + d] = ls * (1.0f / 16.0f); } }
;     __syncthreads();
	v_lshlrev_b32_e32 v52, 16, v46
	v_and_b32_e32 v46, 0xffff0000, v46
	v_mul_f32_e32 v46, v161, v46
	v_fmac_f32_e32 v46, v163, v52
	v_lshlrev_b32_e32 v52, 16, v47
	v_fmac_f32_e32 v46, v160, v52
	v_and_b32_e32 v47, 0xffff0000, v47
	v_fmac_f32_e32 v46, v159, v47
	v_lshlrev_b32_e32 v47, 16, v48
	v_fmac_f32_e32 v46, v122, v47
	v_and_b32_e32 v47, 0xffff0000, v48
	v_fmac_f32_e32 v46, v121, v47
	v_lshlrev_b32_e32 v47, 16, v49
	v_fmac_f32_e32 v46, v120, v47
	v_and_b32_e32 v47, 0xffff0000, v49
	v_fmac_f32_e32 v46, v119, v47
	v_lshlrev_b32_e32 v47, 16, v42
	v_and_b32_e32 v42, 0xffff0000, v42
	v_mul_f32_e32 v42, v118, v42
	v_fmac_f32_e32 v42, v123, v47
	v_lshlrev_b32_e32 v47, 16, v43
	v_fmac_f32_e32 v42, v117, v47
	v_and_b32_e32 v43, 0xffff0000, v43
	v_fmac_f32_e32 v42, v116, v43
	v_lshlrev_b32_e32 v43, 16, v44
	v_fmac_f32_e32 v42, v115, v43
	v_and_b32_e32 v43, 0xffff0000, v44
	v_fmac_f32_e32 v42, v114, v43
	v_lshlrev_b32_e32 v43, 16, v45
	v_fmac_f32_e32 v42, v113, v43
	v_and_b32_e32 v43, 0xffff0000, v45
	v_add_f32_e32 v46, v162, v46
	v_fmac_f32_e32 v42, v112, v43
	v_add_f32_e32 v42, v46, v42
	v_mul_f32_e64 v43, |v42|, s77
	v_exp_f32_e32 v43, v43
	v_cndmask_b32_e32 v44, 0, v238, vcc
	v_sub_f32_e32 v44, v51, v44
	v_sub_f32_e32 v44, v50, v44
	v_add_f32_e32 v43, 1.0, v43
	v_cmp_gt_f32_e32 vcc, s76, v43
	v_mul_f32_e32 v44, 0x3d800000, v44
	ds_write_b32 v53, v44 offset:2080
	v_cndmask_b32_e64 v45, 0, 32, vcc
	v_ldexp_f32 v43, v43, v45
	v_log_f32_e32 v43, v43
	v_min_f32_e32 v42, 0, v42
	v_mul_f32_e32 v44, 0x3f317217, v43
	v_fma_f32 v44, v43, s81, -v44
	v_fmac_f32_e32 v44, 0x3377d1cf, v43
	v_fmac_f32_e32 v44, 0x3f317217, v43
	v_cmp_lt_f32_e64 s[38:39], |v43|, s82
	s_nop 1
	v_cndmask_b32_e64 v43, v43, v44, s[38:39]
	s_waitcnt vmcnt(8)
	v_lshlrev_b32_e32 v44, 16, v38
	v_and_b32_e32 v38, 0xffff0000, v38
	v_mul_f32_e32 v38, v161, v38
	v_fmac_f32_e32 v38, v163, v44
	v_lshlrev_b32_e32 v44, 16, v39
	v_fmac_f32_e32 v38, v160, v44
	v_and_b32_e32 v39, 0xffff0000, v39
	v_fmac_f32_e32 v38, v159, v39
	v_lshlrev_b32_e32 v39, 16, v40
	v_fmac_f32_e32 v38, v122, v39
	v_and_b32_e32 v39, 0xffff0000, v40
	v_fmac_f32_e32 v38, v121, v39
	v_lshlrev_b32_e32 v39, 16, v41
	v_fmac_f32_e32 v38, v120, v39
	v_and_b32_e32 v39, 0xffff0000, v41
	v_fmac_f32_e32 v38, v119, v39
	v_lshlrev_b32_e32 v39, 16, v34
	v_and_b32_e32 v34, 0xffff0000, v34
	v_mul_f32_e32 v34, v118, v34
	v_fmac_f32_e32 v34, v123, v39
	v_lshlrev_b32_e32 v39, 16, v35
	v_fmac_f32_e32 v34, v117, v39
	v_and_b32_e32 v35, 0xffff0000, v35
	v_fmac_f32_e32 v34, v116, v35
	v_lshlrev_b32_e32 v35, 16, v36
	v_fmac_f32_e32 v34, v115, v35
	v_and_b32_e32 v35, 0xffff0000, v36
	v_fmac_f32_e32 v34, v114, v35
	v_lshlrev_b32_e32 v35, 16, v37
	v_fmac_f32_e32 v34, v113, v35
	v_and_b32_e32 v35, 0xffff0000, v37
	v_add_f32_e32 v38, v162, v38
	v_fmac_f32_e32 v34, v112, v35
	v_add_f32_e32 v34, v38, v34
	v_mul_f32_e64 v35, |v34|, s77
	v_exp_f32_e32 v35, v35
	v_cndmask_b32_e32 v36, 0, v238, vcc
	v_sub_f32_e32 v36, v43, v36
	v_sub_f32_e32 v36, v42, v36
	v_add_f32_e32 v35, 1.0, v35
	v_cmp_gt_f32_e32 vcc, s76, v35
	v_mul_f32_e32 v36, 0x3d800000, v36
	ds_write_b32 v53, v36 offset:4160
	v_cndmask_b32_e64 v37, 0, 32, vcc
	v_ldexp_f32 v35, v35, v37
	v_log_f32_e32 v35, v35
	v_min_f32_e32 v34, 0, v34
	v_add_u32_e32 v44, 47, v155
	v_mul_f32_e32 v36, 0x3f317217, v35
	v_fma_f32 v36, v35, s81, -v36
	v_fmac_f32_e32 v36, 0x3377d1cf, v35
	v_fmac_f32_e32 v36, 0x3f317217, v35
	v_cmp_lt_f32_e64 s[38:39], |v35|, s82
	s_nop 1
	v_cndmask_b32_e64 v35, v35, v36, s[38:39]
	s_waitcnt vmcnt(6)
	v_lshlrev_b32_e32 v36, 16, v30
	v_and_b32_e32 v30, 0xffff0000, v30
	v_mul_f32_e32 v30, v161, v30
	v_fmac_f32_e32 v30, v163, v36
	v_lshlrev_b32_e32 v36, 16, v31
	v_fmac_f32_e32 v30, v160, v36
	v_and_b32_e32 v31, 0xffff0000, v31
	v_fmac_f32_e32 v30, v159, v31
	v_lshlrev_b32_e32 v31, 16, v32
	v_fmac_f32_e32 v30, v122, v31
	v_and_b32_e32 v31, 0xffff0000, v32
	v_fmac_f32_e32 v30, v121, v31
	v_lshlrev_b32_e32 v31, 16, v33
	v_fmac_f32_e32 v30, v120, v31
	v_and_b32_e32 v31, 0xffff0000, v33
	v_fmac_f32_e32 v30, v119, v31
	v_lshlrev_b32_e32 v31, 16, v26
	v_and_b32_e32 v26, 0xffff0000, v26
	v_mul_f32_e32 v26, v118, v26
	v_fmac_f32_e32 v26, v123, v31
	v_lshlrev_b32_e32 v31, 16, v27
	v_fmac_f32_e32 v26, v117, v31
	v_and_b32_e32 v27, 0xffff0000, v27
	v_fmac_f32_e32 v26, v116, v27
	v_lshlrev_b32_e32 v27, 16, v28
	v_fmac_f32_e32 v26, v115, v27
	v_and_b32_e32 v27, 0xffff0000, v28
	v_fmac_f32_e32 v26, v114, v27
	v_lshlrev_b32_e32 v27, 16, v29
	v_fmac_f32_e32 v26, v113, v27
	v_and_b32_e32 v27, 0xffff0000, v29
	v_add_f32_e32 v30, v162, v30
	v_fmac_f32_e32 v26, v112, v27
	v_add_f32_e32 v26, v30, v26
	v_mul_f32_e64 v27, |v26|, s77
	v_exp_f32_e32 v27, v27
	v_cndmask_b32_e32 v28, 0, v238, vcc
	v_sub_f32_e32 v28, v35, v28
	v_sub_f32_e32 v28, v34, v28
	v_add_f32_e32 v27, 1.0, v27
	v_cmp_gt_f32_e32 vcc, s76, v27
	v_mul_f32_e32 v28, 0x3d800000, v28
	ds_write_b32 v53, v28 offset:6240
	v_cndmask_b32_e64 v29, 0, 32, vcc
	v_ldexp_f32 v27, v27, v29
	v_log_f32_e32 v27, v27
	v_min_f32_e32 v26, 0, v26
	v_mul_f32_e32 v28, 0x3f317217, v27
	v_fma_f32 v28, v27, s81, -v28
	v_fmac_f32_e32 v28, 0x3377d1cf, v27
	v_fmac_f32_e32 v28, 0x3f317217, v27
	v_cmp_lt_f32_e64 s[38:39], |v27|, s82
	s_nop 1
	v_cndmask_b32_e64 v27, v27, v28, s[38:39]
	s_waitcnt vmcnt(4)
; __device__ __forceinline__ float bflo(unsigned w) { return __uint_as_float(w << 16); }
; __device__ __forceinline__ float bfhi(unsigned w) { return __uint_as_float(w & 0xffff0000u); }
; __device__ __forceinline__ void gla_gcum(LAS unsigned char* lds, const GlaArgs& A, int t0, int h, int tid) {
;     ...
;       for (int e = 0; e < 8; ++e) { const int i = i0 + 8 * e; const u32x4 a0 = al0[e], a1 = al1[e];
;           float x = ab;
;           x += bflo(a0.x) * au[0] + bfhi(a0.x) * au[1] + bflo(a0.y) * au[2] + bfhi(a0.y) * au[3] + bflo(a0.z) * au[4] + bfhi(a0.z) * au[5] + bflo(a0.w) * au[6] + bfhi(a0.w) * au[7];
;           x += bflo(a1.x) * au[8] + bfhi(a1.x) * au[9] + bflo(a1.y) * au[10] + bfhi(a1.y) * au[11] + bflo(a1.z) * au[12] + bfhi(a1.z) * au[13] + bflo(a1.w) * au[14] + bfhi(a1.w) * au[15];
;           const float ls = fminf(x, 0.f) - __logf(1.f + __expf(-fabsf(x)));
;           GC[i * 65 + d] = ls * (1.0f / 16.0f); } }
;     __syncthreads();
	v_lshlrev_b32_e32 v28, 16, v22
	v_and_b32_e32 v22, 0xffff0000, v22
	v_mul_f32_e32 v22, v161, v22
	v_fmac_f32_e32 v22, v163, v28
	v_lshlrev_b32_e32 v28, 16, v23
	v_fmac_f32_e32 v22, v160, v28
	v_and_b32_e32 v23, 0xffff0000, v23
	v_fmac_f32_e32 v22, v159, v23
	v_lshlrev_b32_e32 v23, 16, v24
	v_fmac_f32_e32 v22, v122, v23
	v_and_b32_e32 v23, 0xffff0000, v24
	v_fmac_f32_e32 v22, v121, v23
	v_lshlrev_b32_e32 v23, 16, v25
	v_fmac_f32_e32 v22, v120, v23
	v_and_b32_e32 v23, 0xffff0000, v25
	v_fmac_f32_e32 v22, v119, v23
	v_lshlrev_b32_e32 v23, 16, v18
	v_and_b32_e32 v18, 0xffff0000, v18
	v_mul_f32_e32 v18, v118, v18
	v_fmac_f32_e32 v18, v123, v23
	v_lshlrev_b32_e32 v23, 16, v19
	v_fmac_f32_e32 v18, v117, v23
	v_and_b32_e32 v19, 0xffff0000, v19
	v_fmac_f32_e32 v18, v116, v19
	v_lshlrev_b32_e32 v19, 16, v20
	v_fmac_f32_e32 v18, v115, v19
	v_and_b32_e32 v19, 0xffff0000, v20
	v_fmac_f32_e32 v18, v114, v19
	v_lshlrev_b32_e32 v19, 16, v21
	v_fmac_f32_e32 v18, v113, v19
	v_and_b32_e32 v19, 0xffff0000, v21
	v_add_f32_e32 v22, v162, v22
	v_fmac_f32_e32 v18, v112, v19
	v_add_f32_e32 v18, v22, v18
	v_mul_f32_e64 v19, |v18|, s77
	v_exp_f32_e32 v19, v19
	v_cndmask_b32_e32 v20, 0, v238, vcc
	v_sub_f32_e32 v20, v27, v20
	v_sub_f32_e32 v20, v26, v20
	v_add_f32_e32 v19, 1.0, v19
	v_cmp_gt_f32_e32 vcc, s76, v19
	v_mul_f32_e32 v20, 0x3d800000, v20
	ds_write_b32 v53, v20 offset:8320
	v_cndmask_b32_e64 v21, 0, 32, vcc
	v_ldexp_f32 v19, v19, v21
	v_log_f32_e32 v19, v19
	v_min_f32_e32 v18, 0, v18
	v_add_u32_e32 v22, -1, v155
	v_mul_f32_e32 v20, 0x3f317217, v19
	v_fma_f32 v20, v19, s81, -v20
	v_fmac_f32_e32 v20, 0x3377d1cf, v19
	v_fmac_f32_e32 v20, 0x3f317217, v19
	v_cmp_lt_f32_e64 s[38:39], |v19|, s82
	s_nop 1
	v_cndmask_b32_e64 v19, v19, v20, s[38:39]
	s_waitcnt vmcnt(2)
	v_lshlrev_b32_e32 v20, 16, v6
	v_and_b32_e32 v6, 0xffff0000, v6
	v_mul_f32_e32 v6, v161, v6
	v_fmac_f32_e32 v6, v163, v20
	v_lshlrev_b32_e32 v20, 16, v7
	v_fmac_f32_e32 v6, v160, v20
	v_and_b32_e32 v7, 0xffff0000, v7
	v_fmac_f32_e32 v6, v159, v7
	v_lshlrev_b32_e32 v7, 16, v8
	v_fmac_f32_e32 v6, v122, v7
	v_and_b32_e32 v7, 0xffff0000, v8
	v_fmac_f32_e32 v6, v121, v7
	v_lshlrev_b32_e32 v7, 16, v9
	v_fmac_f32_e32 v6, v120, v7
	v_and_b32_e32 v7, 0xffff0000, v9
	v_fmac_f32_e32 v6, v119, v7
	v_lshlrev_b32_e32 v7, 16, v2
	v_and_b32_e32 v2, 0xffff0000, v2
	v_mul_f32_e32 v2, v118, v2
	v_fmac_f32_e32 v2, v123, v7
	v_lshlrev_b32_e32 v7, 16, v3
	v_fmac_f32_e32 v2, v117, v7
	v_and_b32_e32 v3, 0xffff0000, v3
	v_fmac_f32_e32 v2, v116, v3
	v_lshlrev_b32_e32 v3, 16, v4
	v_fmac_f32_e32 v2, v115, v3
	v_and_b32_e32 v3, 0xffff0000, v4
	v_fmac_f32_e32 v2, v114, v3
	v_lshlrev_b32_e32 v3, 16, v5
	v_fmac_f32_e32 v2, v113, v3
	v_and_b32_e32 v3, 0xffff0000, v5
	v_add_f32_e32 v6, v162, v6
	v_fmac_f32_e32 v2, v112, v3
	v_add_f32_e32 v2, v6, v2
	v_mul_f32_e64 v3, |v2|, s77
	v_exp_f32_e32 v3, v3
	v_cndmask_b32_e32 v4, 0, v238, vcc
	v_sub_f32_e32 v4, v19, v4
	v_sub_f32_e32 v4, v18, v4
	v_add_f32_e32 v3, 1.0, v3
	v_cmp_gt_f32_e32 vcc, s76, v3
	v_mul_f32_e32 v4, 0x3d800000, v4
	ds_write_b32 v53, v4 offset:10400
	v_cndmask_b32_e64 v5, 0, 32, vcc
	v_ldexp_f32 v3, v3, v5
	v_log_f32_e32 v3, v3
	s_waitcnt vmcnt(0)
	v_and_b32_e32 v5, 0xffff0000, v14
	v_mul_f32_e32 v5, v161, v5
	v_and_b32_e32 v6, 0xffff0000, v10
	v_mul_f32_e32 v4, 0x3f317217, v3
	v_fma_f32 v4, v3, s81, -v4
	v_fmac_f32_e32 v4, 0x3377d1cf, v3
	v_fmac_f32_e32 v4, 0x3f317217, v3
	v_cmp_lt_f32_e64 s[38:39], |v3|, s82
	v_mul_f32_e32 v6, v118, v6
	v_min_f32_e32 v2, 0, v2
	v_cndmask_b32_e64 v3, v3, v4, s[38:39]
	v_lshlrev_b32_e32 v4, 16, v14
	v_fmac_f32_e32 v5, v163, v4
	v_lshlrev_b32_e32 v4, 16, v15
	v_fmac_f32_e32 v5, v160, v4
	v_and_b32_e32 v4, 0xffff0000, v15
	v_fmac_f32_e32 v5, v159, v4
	v_lshlrev_b32_e32 v4, 16, v16
	v_fmac_f32_e32 v5, v122, v4
	v_and_b32_e32 v4, 0xffff0000, v16
	v_fmac_f32_e32 v5, v121, v4
	v_lshlrev_b32_e32 v4, 16, v17
	v_fmac_f32_e32 v5, v120, v4
	v_and_b32_e32 v4, 0xffff0000, v17
	v_fmac_f32_e32 v5, v119, v4
	v_add_f32_e32 v4, v162, v5
	v_lshlrev_b32_e32 v5, 16, v10
	v_fmac_f32_e32 v6, v123, v5
	v_lshlrev_b32_e32 v5, 16, v11
	v_fmac_f32_e32 v6, v117, v5
	v_and_b32_e32 v5, 0xffff0000, v11
	v_fmac_f32_e32 v6, v116, v5
	v_lshlrev_b32_e32 v5, 16, v12
	v_fmac_f32_e32 v6, v115, v5
	v_and_b32_e32 v5, 0xffff0000, v12
	v_fmac_f32_e32 v6, v114, v5
	v_lshlrev_b32_e32 v5, 16, v13
	v_fmac_f32_e32 v6, v113, v5
	v_and_b32_e32 v5, 0xffff0000, v13
	v_fmac_f32_e32 v6, v112, v5
	v_add_f32_e32 v4, v4, v6
	v_mul_f32_e64 v5, |v4|, s77
	v_exp_f32_e32 v5, v5
	v_cndmask_b32_e32 v6, 0, v238, vcc
	v_sub_f32_e32 v3, v3, v6
	v_sub_f32_e32 v2, v2, v3
	v_add_f32_e32 v3, 1.0, v5
	v_cmp_gt_f32_e32 vcc, s76, v3
	v_mul_f32_e32 v2, 0x3d800000, v2
	ds_write_b32 v53, v2 offset:12480
	v_cndmask_b32_e64 v5, 0, 32, vcc
	v_ldexp_f32 v3, v3, v5
	v_log_f32_e32 v3, v3
	v_min_f32_e32 v2, 0, v4
	v_add_u32_e32 v159, s62, v134
	v_add_u32_e32 v18, -3, v155
	v_mul_f32_e32 v4, 0x3f317217, v3
	v_fma_f32 v4, v3, s81, -v4
	v_fmac_f32_e32 v4, 0x3377d1cf, v3
	v_fmac_f32_e32 v4, 0x3f317217, v3
	v_cmp_lt_f32_e64 s[38:39], |v3|, s82
	v_add_u32_e32 v20, -2, v155
	v_add_u32_e32 v26, 32, v159
	v_cndmask_b32_e64 v3, v3, v4, s[38:39]
	v_cndmask_b32_e32 v4, 0, v238, vcc
	v_sub_f32_e32 v3, v3, v4
	v_sub_f32_e32 v2, v2, v3
	v_mul_f32_e32 v2, 0x3d800000, v2
	ds_write_b32 v53, v2 offset:14560
	s_waitcnt lgkmcnt(0)
	s_barrier
; __device__ __forceinline__ void gla_conv8(f32x4 (&out)[8], const bf16_t* Ug, const float* conv, int t0, int s0, int i0, int c0) {
;     f32x4 w[4];
; #pragma unroll
;     for (int j = 0; j < 4; ++j) w[j] = *(const f32x4*)(conv + j * 1024 + c0);
;     u32x2 raw[8][4];
; #pragma unroll
;     for (int e = 0; e < 8; ++e)
; #pragma unroll
;         for (int j = 0; j < 4; ++j) { const int i = i0 + 8 * e, ds = 3 - j; const bool ok = (s0 + i - ds) >= 0; raw[e][j] = *(const u32x2*)(Ug + (size_t)(ok ? t0 + i - ds : t0) * 1792 + c0); }
; __device__ __forceinline__ void gla_gcum(LAS unsigned char* lds, const GlaArgs& A, int t0, int h, int tid) {
;     ...
;     { const int lane = tid & 63, wave = tid >> 6;
; #pragma unroll
;       for (int dd = 0; dd < 8; ++dd) { const int d = wave * 8 + dd; float x = GC[lane * 65 + d];
; #pragma unroll
;           for (int o = 1; o < 64; o <<= 1) { const float y = __shfl_up(x, o); if (lane >= o) x += y; }
;           GC[lane * 65 + d] = x; } }
;     __syncthreads();
	ds_read2_b32 v[2:3], v145 offset1:1
	ds_read2_b32 v[4:5], v145 offset0:6 offset1:7
	ds_read2_b32 v[6:7], v145 offset0:2 offset1:3
	ds_read2_b32 v[12:13], v145 offset0:4 offset1:5
	s_waitcnt lgkmcnt(0)
	v_add_f32_dpp v2, v2, v2 row_shr:1 row_mask:0xf bank_mask:0xf
	v_add_f32_dpp v3, v3, v3 row_shr:1 row_mask:0xf bank_mask:0xf
	v_add_f32_dpp v6, v6, v6 row_shr:1 row_mask:0xf bank_mask:0xf
	s_add_i32 s38, s97, s62
	v_add_f32_dpp v7, v7, v7 row_shr:1 row_mask:0xf bank_mask:0xf
	v_add_f32_dpp v12, v12, v12 row_shr:1 row_mask:0xf bank_mask:0xf
	v_add_f32_dpp v13, v13, v13 row_shr:1 row_mask:0xf bank_mask:0xf
	v_mov_b32_e32 v170, s38
	v_add_f32_dpp v4, v4, v4 row_shr:1 row_mask:0xf bank_mask:0xf
	v_add_f32_dpp v5, v5, v5 row_shr:1 row_mask:0xf bank_mask:0xf
	v_add_f32_dpp v2, v2, v2 row_shr:2 row_mask:0xf bank_mask:0xf
	v_cmp_gt_i32_e32 vcc, 3, v159
	v_add_f32_dpp v3, v3, v3 row_shr:2 row_mask:0xf bank_mask:0xf
	v_add_f32_dpp v6, v6, v6 row_shr:2 row_mask:0xf bank_mask:0xf
	v_add_f32_dpp v7, v7, v7 row_shr:2 row_mask:0xf bank_mask:0xf
	v_cndmask_b32_e32 v18, v18, v170, vcc
	v_add_f32_dpp v12, v12, v12 row_shr:2 row_mask:0xf bank_mask:0xf
	v_add_f32_dpp v13, v13, v13 row_shr:2 row_mask:0xf bank_mask:0xf
	v_add_f32_dpp v4, v4, v4 row_shr:2 row_mask:0xf bank_mask:0xf
	v_cmp_gt_i32_e32 vcc, 2, v159
	v_add_f32_dpp v5, v5, v5 row_shr:2 row_mask:0xf bank_mask:0xf
	v_add_f32_dpp v2, v2, v2 row_shr:4 row_mask:0xf bank_mask:0xf
	v_add_f32_dpp v3, v3, v3 row_shr:4 row_mask:0xf bank_mask:0xf
	v_mad_i64_i32 v[18:19], s[38:39], v18, s80, v[106:107]
	v_add_f32_dpp v6, v6, v6 row_shr:4 row_mask:0xf bank_mask:0xf
	v_add_f32_dpp v7, v7, v7 row_shr:4 row_mask:0xf bank_mask:0xf
	v_add_f32_dpp v12, v12, v12 row_shr:4 row_mask:0xf bank_mask:0xf
	v_cndmask_b32_e32 v20, v20, v170, vcc
	v_add_f32_dpp v13, v13, v13 row_shr:4 row_mask:0xf bank_mask:0xf
	v_add_f32_dpp v4, v4, v4 row_shr:4 row_mask:0xf bank_mask:0xf
	v_add_f32_dpp v5, v5, v5 row_shr:4 row_mask:0xf bank_mask:0xf
	v_cmp_gt_i32_e32 vcc, 1, v159
	v_add_f32_dpp v2, v2, v2 row_shr:8 row_mask:0xf bank_mask:0xf
	v_add_f32_dpp v3, v3, v3 row_shr:8 row_mask:0xf bank_mask:0xf
	v_add_f32_dpp v6, v6, v6 row_shr:8 row_mask:0xf bank_mask:0xf
	v_cndmask_b32_e32 v22, v22, v170, vcc
	v_add_f32_dpp v7, v7, v7 row_shr:8 row_mask:0xf bank_mask:0xf
	v_add_f32_dpp v12, v12, v12 row_shr:8 row_mask:0xf bank_mask:0xf
	v_add_f32_dpp v13, v13, v13 row_shr:8 row_mask:0xf bank_mask:0xf
	v_cmp_gt_i32_e32 vcc, 0, v159
	v_add_f32_dpp v4, v4, v4 row_shr:8 row_mask:0xf bank_mask:0xf
	v_add_f32_dpp v5, v5, v5 row_shr:8 row_mask:0xf bank_mask:0xf
	v_add_f32_dpp v2, v2, v2 row_bcast:15 row_mask:0xa bank_mask:0xf
	v_cndmask_b32_e32 v24, v155, v170, vcc
	v_add_f32_dpp v3, v3, v3 row_bcast:15 row_mask:0xa bank_mask:0xf
	v_add_f32_dpp v6, v6, v6 row_bcast:15 row_mask:0xa bank_mask:0xf
	v_add_f32_dpp v7, v7, v7 row_bcast:15 row_mask:0xa bank_mask:0xf
	v_add_f32_dpp v12, v12, v12 row_bcast:15 row_mask:0xa bank_mask:0xf
	v_add_f32_dpp v13, v13, v13 row_bcast:15 row_mask:0xa bank_mask:0xf
	v_add_f32_dpp v4, v4, v4 row_bcast:15 row_mask:0xa bank_mask:0xf
	v_add_f32_dpp v5, v5, v5 row_bcast:15 row_mask:0xa bank_mask:0xf
	v_add_f32_dpp v2, v2, v2 row_bcast:31 row_mask:0xc bank_mask:0xf
	v_add_f32_dpp v3, v3, v3 row_bcast:31 row_mask:0xc bank_mask:0xf
	v_add_f32_dpp v6, v6, v6 row_bcast:31 row_mask:0xc bank_mask:0xf
	v_add_f32_dpp v7, v7, v7 row_bcast:31 row_mask:0xc bank_mask:0xf
	v_add_f32_dpp v12, v12, v12 row_bcast:31 row_mask:0xc bank_mask:0xf
	v_add_f32_dpp v13, v13, v13 row_bcast:31 row_mask:0xc bank_mask:0xf
	v_add_f32_dpp v4, v4, v4 row_bcast:31 row_mask:0xc bank_mask:0xf
	v_add_f32_dpp v5, v5, v5 row_bcast:31 row_mask:0xc bank_mask:0xf
	s_nop 1
	ds_write2_b32 v145, v2, v3 offset1:1
	ds_write2_b32 v145, v6, v7 offset0:2 offset1:3
	ds_write2_b32 v145, v12, v13 offset0:4 offset1:5
	ds_write2_b32 v145, v4, v5 offset0:6 offset1:7
	s_waitcnt lgkmcnt(0)
	s_barrier
	global_load_dwordx4 v[14:17], v[88:89], off
	global_load_dwordx4 v[10:13], v[100:101], off
	global_load_dwordx4 v[6:9], v[102:103], off
	global_load_dwordx4 v[2:5], v[104:105], off
	v_mad_i64_i32 v[20:21], s[38:39], v20, s80, v[106:107]
	v_mad_i64_i32 v[22:23], s[38:39], v22, s80, v[106:107]
	v_mad_i64_i32 v[24:25], s[38:39], v24, s80, v[106:107]
	global_load_dwordx2 v[160:161], v[18:19], off
	global_load_dwordx2 v[162:163], v[20:21], off
	global_load_dwordx2 v[164:165], v[22:23], off
	global_load_dwordx2 v[166:167], v[24:25], off
	v_add_u32_e32 v24, 8, v159
	v_add_u32_e32 v18, 5, v155
	v_cmp_gt_i32_e32 vcc, 3, v24
	v_add_u32_e32 v20, 6, v155
	v_add_u32_e32 v22, 7, v155
	v_cndmask_b32_e32 v18, v18, v170, vcc
	v_cmp_gt_i32_e32 vcc, 2, v24
	v_mad_i64_i32 v[18:19], s[38:39], v18, s80, v[106:107]
	s_nop 0
	v_cndmask_b32_e32 v20, v20, v170, vcc
	v_cmp_gt_i32_e32 vcc, 1, v24
	v_mad_i64_i32 v[20:21], s[38:39], v20, s80, v[106:107]
	s_nop 0
	v_cndmask_b32_e32 v22, v22, v170, vcc
	v_cmp_gt_i32_e32 vcc, 0, v24
	v_mad_i64_i32 v[22:23], s[38:39], v22, s80, v[106:107]
	s_nop 0
	v_cndmask_b32_e32 v24, v111, v170, vcc
	v_mad_i64_i32 v[24:25], s[38:39], v24, s80, v[106:107]
	global_load_dwordx2 v[50:51], v[18:19], off
	global_load_dwordx2 v[38:39], v[20:21], off
	global_load_dwordx2 v[36:37], v[22:23], off
	global_load_dwordx2 v[32:33], v[24:25], off
	v_add_u32_e32 v24, 16, v159
	v_add_u32_e32 v18, 13, v155
	v_cmp_gt_i32_e32 vcc, 3, v24
	v_add_u32_e32 v20, 14, v155
	v_add_u32_e32 v22, 15, v155
	v_cndmask_b32_e32 v18, v18, v170, vcc
	v_cmp_gt_i32_e32 vcc, 2, v24
	v_mad_i64_i32 v[18:19], s[38:39], v18, s80, v[106:107]
	s_nop 0
	v_cndmask_b32_e32 v20, v20, v170, vcc
	v_cmp_gt_i32_e32 vcc, 1, v24
; __device__ __forceinline__ float bflo(unsigned w) { return __uint_as_float(w << 16); }
; __device__ __forceinline__ float bfhi(unsigned w) { return __uint_as_float(w & 0xffff0000u); }
; __device__ __forceinline__ void gla_conv8(f32x4 (&out)[8], const bf16_t* Ug, const float* conv, int t0, int s0, int i0, int c0) {
;     f32x4 w[4];
; #pragma unroll
;     for (int j = 0; j < 4; ++j) w[j] = *(const f32x4*)(conv + j * 1024 + c0);
;     u32x2 raw[8][4];
; #pragma unroll
;     for (int e = 0; e < 8; ++e)
; #pragma unroll
;         for (int j = 0; j < 4; ++j) { const int i = i0 + 8 * e, ds = 3 - j; const bool ok = (s0 + i - ds) >= 0; raw[e][j] = *(const u32x2*)(Ug + (size_t)(ok ? t0 + i - ds : t0) * 1792 + c0); }
; #pragma unroll
;     for (int e = 0; e < 8; ++e) { const int i = i0 + 8 * e; f32x4 a = (f32x4){0.f, 0.f, 0.f, 0.f};
; #pragma unroll
;         for (int j = 0; j < 4; ++j) { const int ds = 3 - j; const float mk = ((s0 + i - ds) >= 0) ? 1.0f : 0.0f; const u32x2 r = raw[e][j];
;             a += (w[j] * mk) * (f32x4){bflo(r.x), bfhi(r.x), bflo(r.y), bfhi(r.y)}; }
	v_mad_i64_i32 v[20:21], s[38:39], v20, s80, v[106:107]
	s_nop 0
	v_cndmask_b32_e32 v22, v22, v170, vcc
	v_cmp_gt_i32_e32 vcc, 0, v24
	v_mad_i64_i32 v[22:23], s[38:39], v22, s80, v[106:107]
	s_nop 0
	v_cndmask_b32_e32 v24, v110, v170, vcc
	v_mad_i64_i32 v[24:25], s[38:39], v24, s80, v[106:107]
	global_load_dwordx2 v[122:123], v[18:19], off
	global_load_dwordx2 v[120:121], v[20:21], off
	global_load_dwordx2 v[118:119], v[22:23], off
	global_load_dwordx2 v[116:117], v[24:25], off
	v_add_u32_e32 v24, 24, v159
	v_add_u32_e32 v18, 21, v155
	v_cmp_gt_i32_e32 vcc, 3, v24
	v_add_u32_e32 v20, 22, v155
	v_add_u32_e32 v22, 23, v155
	v_cndmask_b32_e32 v18, v18, v170, vcc
	v_cmp_gt_i32_e32 vcc, 2, v24
	v_mad_i64_i32 v[18:19], s[38:39], v18, s80, v[106:107]
	s_nop 0
	v_cndmask_b32_e32 v20, v20, v170, vcc
	v_cmp_gt_i32_e32 vcc, 1, v24
	v_mad_i64_i32 v[20:21], s[38:39], v20, s80, v[106:107]
	s_nop 0
	v_cndmask_b32_e32 v22, v22, v170, vcc
	v_cmp_gt_i32_e32 vcc, 0, v24
	v_mad_i64_i32 v[22:23], s[38:39], v22, s80, v[106:107]
	s_nop 0
	v_cndmask_b32_e32 v24, v109, v170, vcc
	v_mad_i64_i32 v[24:25], s[38:39], v24, s80, v[106:107]
	global_load_dwordx2 v[34:35], v[18:19], off
	global_load_dwordx2 v[30:31], v[20:21], off
	global_load_dwordx2 v[28:29], v[22:23], off
	s_nop 0
	global_load_dwordx2 v[24:25], v[24:25], off
	v_add_u32_e32 v18, 29, v155
	v_cmp_gt_i32_e32 vcc, 3, v26
	v_add_u32_e32 v20, 30, v155
	v_add_u32_e32 v22, 31, v155
	v_cndmask_b32_e32 v18, v18, v170, vcc
	v_cmp_gt_i32_e32 vcc, 2, v26
	v_mad_i64_i32 v[18:19], s[38:39], v18, s80, v[106:107]
	s_nop 0
	v_cndmask_b32_e32 v20, v20, v170, vcc
	v_cmp_gt_i32_e32 vcc, 1, v26
	v_mad_i64_i32 v[20:21], s[38:39], v20, s80, v[106:107]
	s_nop 0
	v_cndmask_b32_e32 v22, v22, v170, vcc
	v_cmp_gt_i32_e32 vcc, 0, v26
	v_mad_i64_i32 v[22:23], s[38:39], v22, s80, v[106:107]
	s_nop 0
	v_cndmask_b32_e32 v26, v108, v170, vcc
	v_mad_i64_i32 v[26:27], s[38:39], v26, s80, v[106:107]
	global_load_dwordx2 v[114:115], v[18:19], off
	global_load_dwordx2 v[112:113], v[20:21], off
	global_load_dwordx2 v[110:111], v[22:23], off
	global_load_dwordx2 v[108:109], v[26:27], off
	v_add_u32_e32 v22, 40, v159
	v_add_u32_e32 v18, 37, v155
	v_cmp_gt_i32_e32 vcc, 3, v22
	v_add_u32_e32 v20, 38, v155
	v_add_u32_e32 v23, 39, v155
	v_cndmask_b32_e32 v18, v18, v170, vcc
	v_cmp_gt_i32_e32 vcc, 2, v22
	v_mad_i64_i32 v[18:19], s[38:39], v18, s80, v[106:107]
	s_nop 0
	v_cndmask_b32_e32 v20, v20, v170, vcc
	v_cmp_gt_i32_e32 vcc, 1, v22
	v_mad_i64_i32 v[20:21], s[38:39], v20, s80, v[106:107]
	s_nop 0
	v_cndmask_b32_e32 v23, v23, v170, vcc
	v_cmp_gt_i32_e32 vcc, 0, v22
	v_mad_i64_i32 v[40:41], s[38:39], v23, s80, v[106:107]
	s_nop 0
	v_cndmask_b32_e32 v22, v158, v170, vcc
	v_add_u32_e32 v46, 48, v159
	v_mad_i64_i32 v[42:43], s[38:39], v22, s80, v[106:107]
	global_load_dwordx2 v[26:27], v[18:19], off
	global_load_dwordx2 v[22:23], v[20:21], off
	s_nop 0
	global_load_dwordx2 v[20:21], v[40:41], off
	global_load_dwordx2 v[18:19], v[42:43], off
	v_add_u32_e32 v40, 45, v155
	v_cmp_gt_i32_e32 vcc, 3, v46
	v_add_u32_e32 v42, 46, v155
	s_waitcnt vmcnt(23)
	v_and_b32_e32 v171, 0xffff0000, v160
	v_cndmask_b32_e32 v40, v40, v170, vcc
	v_cmp_gt_i32_e32 vcc, 2, v46
	v_mad_i64_i32 v[40:41], s[38:39], v40, s80, v[106:107]
	s_nop 0
	v_cndmask_b32_e32 v42, v42, v170, vcc
	v_cmp_gt_i32_e32 vcc, 1, v46
	v_mad_i64_i32 v[42:43], s[38:39], v42, s80, v[106:107]
	s_nop 0
	v_cndmask_b32_e32 v44, v44, v170, vcc
	v_cmp_gt_i32_e32 vcc, 0, v46
	v_mad_i64_i32 v[44:45], s[38:39], v44, s80, v[106:107]
	s_nop 0
	v_cndmask_b32_e32 v46, v157, v170, vcc
	v_mad_i64_i32 v[46:47], s[38:39], v46, s80, v[106:107]
	global_load_dwordx2 v[56:57], v[40:41], off
	global_load_dwordx2 v[54:55], v[42:43], off
	global_load_dwordx2 v[52:53], v[44:45], off
	global_load_dwordx2 v[48:49], v[46:47], off
	v_add_u32_e32 v44, 56, v159
	v_add_u32_e32 v40, 53, v155
	v_cmp_gt_i32_e32 vcc, 3, v44
	v_add_u32_e32 v42, 54, v155
	v_add_u32_e32 v45, 55, v155
	v_cndmask_b32_e32 v40, v40, v170, vcc
	v_cmp_gt_i32_e32 vcc, 2, v44
	v_mad_i64_i32 v[40:41], s[38:39], v40, s80, v[106:107]
	s_nop 0
	v_cndmask_b32_e32 v42, v42, v170, vcc
	v_cmp_gt_i32_e32 vcc, 1, v44
	v_mad_i64_i32 v[42:43], s[38:39], v42, s80, v[106:107]
	s_nop 0
	v_cndmask_b32_e32 v45, v45, v170, vcc
	v_cmp_gt_i32_e32 vcc, 0, v44
	v_mad_i64_i32 v[168:169], s[38:39], v45, s80, v[106:107]
	s_nop 0
	v_cndmask_b32_e32 v44, v156, v170, vcc
	v_mad_i64_i32 v[156:157], s[38:39], v44, s80, v[106:107]
	v_cmp_lt_i32_e32 vcc, 2, v159
	global_load_dwordx2 v[46:47], v[40:41], off
	global_load_dwordx2 v[44:45], v[42:43], off
	s_nop 0
	global_load_dwordx2 v[42:43], v[168:169], off
	global_load_dwordx2 v[40:41], v[156:157], off
	v_cndmask_b32_e64 v156, 0, 1.0, vcc
	v_cmp_lt_i32_e32 vcc, 1, v159
	v_pk_mul_f32 v[168:169], v[156:157], v[16:17] op_sel_hi:[0,1]
	v_pk_mul_f32 v[156:157], v[156:157], v[14:15] op_sel_hi:[0,1]
	v_lshlrev_b32_e32 v170, 16, v160
	v_lshlrev_b32_e32 v160, 16, v161
	v_and_b32_e32 v161, 0xffff0000, v161
	v_cndmask_b32_e64 v158, 0, 1.0, vcc
	v_cmp_lt_i32_e32 vcc, 0, v159
	v_pk_fma_f32 v[156:157], v[156:157], v[170:171], 0 op_sel_hi:[1,1,0]
	v_pk_fma_f32 v[160:161], v[168:169], v[160:161], 0 op_sel_hi:[1,1,0]
	v_pk_mul_f32 v[168:169], v[158:159], v[12:13] op_sel_hi:[0,1]
	v_pk_mul_f32 v[170:171], v[158:159], v[10:11] op_sel_hi:[0,1]
	s_waitcnt vmcnt(30)
	v_lshlrev_b32_e32 v172, 16, v162
	v_and_b32_e32 v173, 0xffff0000, v162
	v_lshlrev_b32_e32 v162, 16, v163
	v_and_b32_e32 v163, 0xffff0000, v163
	v_cndmask_b32_e64 v158, 0, 1.0, vcc
	v_cmp_lt_i32_e32 vcc, -1, v159
	v_pk_fma_f32 v[160:161], v[168:169], v[162:163], v[160:161]
	v_pk_fma_f32 v[156:157], v[170:171], v[172:173], v[156:157]
	v_pk_mul_f32 v[162:163], v[158:159], v[8:9] op_sel_hi:[0,1]
	v_pk_mul_f32 v[168:169], v[158:159], v[6:7] op_sel_hi:[0,1]
	s_waitcnt vmcnt(29)
; __device__ __forceinline__ float bflo(unsigned w) { return __uint_as_float(w << 16); }
; __device__ __forceinline__ float bfhi(unsigned w) { return __uint_as_float(w & 0xffff0000u); }
; __device__ __forceinline__ float sigmoidf_(float x) { return __builtin_amdgcn_rcpf(1.0f + __expf(-x)); }
; __device__ __forceinline__ void gla_conv8(f32x4 (&out)[8], const bf16_t* Ug, const float* conv, int t0, int s0, int i0, int c0) {
;     ...
;     for (int e = 0; e < 8; ++e) { const int i = i0 + 8 * e; f32x4 a = (f32x4){0.f, 0.f, 0.f, 0.f};
; #pragma unroll
;         for (int j = 0; j < 4; ++j) { const int ds = 3 - j; const float mk = ((s0 + i - ds) >= 0) ? 1.0f : 0.0f; const u32x2 r = raw[e][j];
;             a += (w[j] * mk) * (f32x4){bflo(r.x), bfhi(r.x), bflo(r.y), bfhi(r.y)}; }
; #pragma unroll
;         for (int q = 0; q < 4; ++q) a[q] = a[q] * sigmoidf_(a[q]);
;         out[e] = a; }
	v_lshlrev_b32_e32 v170, 16, v164
	v_and_b32_e32 v171, 0xffff0000, v164
	v_lshlrev_b32_e32 v164, 16, v165
	v_and_b32_e32 v165, 0xffff0000, v165
	v_cndmask_b32_e64 v158, 0, 1.0, vcc
	v_pk_fma_f32 v[156:157], v[168:169], v[170:171], v[156:157]
	v_pk_fma_f32 v[160:161], v[162:163], v[164:165], v[160:161]
	v_pk_mul_f32 v[164:165], v[158:159], v[2:3] op_sel_hi:[0,1]
	s_waitcnt vmcnt(28)
	v_lshlrev_b32_e32 v168, 16, v166
	v_and_b32_e32 v169, 0xffff0000, v166
	v_pk_fma_f32 v[156:157], v[164:165], v[168:169], v[156:157]
	v_pk_mul_f32 v[162:163], v[158:159], v[4:5] op_sel_hi:[0,1]
	v_mul_f32_e32 v155, 0xbfb8aa3b, v156
	v_exp_f32_e32 v155, v155
	v_mul_f32_e32 v158, 0xbfb8aa3b, v157
	v_exp_f32_e32 v158, v158
	v_lshlrev_b32_e32 v166, 16, v167
	v_and_b32_e32 v167, 0xffff0000, v167
	v_pk_fma_f32 v[160:161], v[162:163], v[166:167], v[160:161]
	v_add_f32_e32 v155, 1.0, v155
	v_rcp_f32_e32 v162, v155
	v_add_f32_e32 v155, 1.0, v158
	v_mul_f32_e32 v158, 0xbfb8aa3b, v160
	v_exp_f32_e32 v158, v158
	v_mul_f32_e32 v163, 0xbfb8aa3b, v161
	v_cmp_lt_i32_e32 vcc, -6, v159
	v_exp_f32_e32 v165, v163
	v_rcp_f32_e32 v163, v155
	v_add_f32_e32 v155, 1.0, v158
	v_cndmask_b32_e64 v158, 0, 1.0, vcc
	v_cmp_lt_i32_e32 vcc, -7, v159
	v_pk_mul_f32 v[166:167], v[158:159], v[16:17] op_sel_hi:[0,1]
	v_pk_mul_f32 v[168:169], v[158:159], v[14:15] op_sel_hi:[0,1]
	s_waitcnt vmcnt(27)
	v_lshlrev_b32_e32 v170, 16, v50
	v_and_b32_e32 v171, 0xffff0000, v50
	v_lshlrev_b32_e32 v50, 16, v51
	v_and_b32_e32 v51, 0xffff0000, v51
	v_cndmask_b32_e64 v158, 0, 1.0, vcc
	v_cmp_lt_i32_e32 vcc, -8, v159
	v_pk_fma_f32 v[168:169], v[168:169], v[170:171], 0 op_sel_hi:[1,1,0]
	v_pk_fma_f32 v[50:51], v[166:167], v[50:51], 0 op_sel_hi:[1,1,0]
	v_pk_mul_f32 v[166:167], v[158:159], v[12:13] op_sel_hi:[0,1]
	v_pk_mul_f32 v[170:171], v[158:159], v[10:11] op_sel_hi:[0,1]
	s_waitcnt vmcnt(26)
	v_lshlrev_b32_e32 v172, 16, v38
	v_and_b32_e32 v173, 0xffff0000, v38
	v_lshlrev_b32_e32 v38, 16, v39
	v_and_b32_e32 v39, 0xffff0000, v39
	v_cndmask_b32_e64 v158, 0, 1.0, vcc
	v_pk_fma_f32 v[38:39], v[166:167], v[38:39], v[50:51]
	v_pk_fma_f32 v[50:51], v[170:171], v[172:173], v[168:169]
	v_pk_mul_f32 v[166:167], v[158:159], v[8:9] op_sel_hi:[0,1]
	s_waitcnt vmcnt(25)
	v_lshlrev_b32_e32 v170, 16, v36
	v_and_b32_e32 v171, 0xffff0000, v36
	v_lshlrev_b32_e32 v36, 16, v37
	v_and_b32_e32 v37, 0xffff0000, v37
	v_cmp_lt_i32_e32 vcc, -9, v159
	v_pk_mul_f32 v[168:169], v[158:159], v[6:7] op_sel_hi:[0,1]
	v_pk_fma_f32 v[36:37], v[166:167], v[36:37], v[38:39]
	v_cndmask_b32_e64 v38, 0, 1.0, vcc
	v_pk_fma_f32 v[50:51], v[168:169], v[170:171], v[50:51]
	v_pk_mul_f32 v[166:167], v[38:39], v[4:5] op_sel_hi:[0,1]
	v_pk_mul_f32 v[38:39], v[38:39], v[2:3] op_sel_hi:[0,1]
	s_waitcnt vmcnt(24)
	v_lshlrev_b32_e32 v168, 16, v32
	v_and_b32_e32 v169, 0xffff0000, v32
	v_pk_fma_f32 v[168:169], v[38:39], v[168:169], v[50:51]
	v_lshlrev_b32_e32 v32, 16, v33
	v_mul_f32_e32 v38, 0xbfb8aa3b, v168
	v_exp_f32_e32 v38, v38
	v_mul_f32_e32 v39, 0xbfb8aa3b, v169
	v_exp_f32_e32 v39, v39
	v_and_b32_e32 v33, 0xffff0000, v33
	v_pk_fma_f32 v[32:33], v[166:167], v[32:33], v[36:37]
	v_add_f32_e32 v36, 1.0, v38
	v_mul_f32_e32 v38, 0xbfb8aa3b, v32
	v_add_f32_e32 v37, 1.0, v39
	v_exp_f32_e32 v38, v38
	v_mul_f32_e32 v39, 0xbfb8aa3b, v33
	v_rcp_f32_e32 v164, v155
	v_add_f32_e32 v155, 1.0, v165
	v_exp_f32_e32 v39, v39
	v_rcp_f32_e32 v165, v155
	v_add_f32_e32 v38, 1.0, v38
	v_cmp_lt_i32_e32 vcc, -14, v159
	v_rcp_f32_e32 v166, v38
	v_add_f32_e32 v38, 1.0, v39
	v_pk_mul_f32 v[50:51], v[156:157], v[162:163]
	v_cndmask_b32_e64 v156, 0, 1.0, vcc
	v_cmp_lt_i32_e32 vcc, -15, v159
	v_rcp_f32_e32 v167, v38
	v_pk_mul_f32 v[38:39], v[160:161], v[164:165]
	v_pk_mul_f32 v[160:161], v[156:157], v[16:17] op_sel_hi:[0,1]
	v_pk_mul_f32 v[156:157], v[156:157], v[14:15] op_sel_hi:[0,1]
	s_waitcnt vmcnt(23)
	v_lshlrev_b32_e32 v162, 16, v122
	v_and_b32_e32 v163, 0xffff0000, v122
	v_lshlrev_b32_e32 v122, 16, v123
	v_and_b32_e32 v123, 0xffff0000, v123
	v_cndmask_b32_e64 v158, 0, 1.0, vcc
	v_pk_fma_f32 v[156:157], v[156:157], v[162:163], 0 op_sel_hi:[1,1,0]
	v_pk_fma_f32 v[122:123], v[160:161], v[122:123], 0 op_sel_hi:[1,1,0]
	v_pk_mul_f32 v[160:161], v[158:159], v[12:13] op_sel_hi:[0,1]
	v_pk_mul_f32 v[162:163], v[158:159], v[10:11] op_sel_hi:[0,1]
	s_waitcnt vmcnt(22)
	v_lshlrev_b32_e32 v164, 16, v120
	v_and_b32_e32 v165, 0xffff0000, v120
	v_lshlrev_b32_e32 v120, 16, v121
	v_and_b32_e32 v121, 0xffff0000, v121
	v_cmp_lt_i32_e32 vcc, -16, v159
	v_pk_fma_f32 v[120:121], v[160:161], v[120:121], v[122:123]
	v_pk_fma_f32 v[122:123], v[162:163], v[164:165], v[156:157]
	v_cndmask_b32_e64 v156, 0, 1.0, vcc
	v_pk_mul_f32 v[160:161], v[156:157], v[8:9] op_sel_hi:[0,1]
	s_waitcnt vmcnt(21)
	v_lshlrev_b32_e32 v162, 16, v118
	v_and_b32_e32 v163, 0xffff0000, v118
	v_lshlrev_b32_e32 v118, 16, v119
	v_and_b32_e32 v119, 0xffff0000, v119
	v_cmp_lt_i32_e32 vcc, s36, v159
	v_pk_mul_f32 v[156:157], v[156:157], v[6:7] op_sel_hi:[0,1]
	v_pk_fma_f32 v[118:119], v[160:161], v[118:119], v[120:121]
	v_cndmask_b32_e64 v120, 0, 1.0, vcc
	s_movk_i32 s36, 0xffea
	v_pk_fma_f32 v[122:123], v[156:157], v[162:163], v[122:123]
	v_pk_mul_f32 v[156:157], v[120:121], v[4:5] op_sel_hi:[0,1]
	s_waitcnt vmcnt(20)
	v_lshlrev_b32_e32 v160, 16, v116
	v_and_b32_e32 v161, 0xffff0000, v116
	v_lshlrev_b32_e32 v116, 16, v117
	v_and_b32_e32 v117, 0xffff0000, v117
	v_cmp_lt_i32_e32 vcc, s36, v159
	s_movk_i32 s36, 0xffe9
	v_pk_mul_f32 v[120:121], v[120:121], v[2:3] op_sel_hi:[0,1]
	v_pk_fma_f32 v[116:117], v[156:157], v[116:117], v[118:119]
	v_cndmask_b32_e64 v156, 0, 1.0, vcc
	v_cmp_lt_i32_e32 vcc, s36, v159
	v_pk_fma_f32 v[120:121], v[120:121], v[160:161], v[122:123]
	v_pk_mul_f32 v[160:161], v[156:157], v[16:17] op_sel_hi:[0,1]
	v_pk_mul_f32 v[156:157], v[156:157], v[14:15] op_sel_hi:[0,1]
	s_waitcnt vmcnt(19)
; __device__ __forceinline__ float bflo(unsigned w) { return __uint_as_float(w << 16); }
; __device__ __forceinline__ float bfhi(unsigned w) { return __uint_as_float(w & 0xffff0000u); }
; __device__ __forceinline__ float sigmoidf_(float x) { return __builtin_amdgcn_rcpf(1.0f + __expf(-x)); }
; __device__ __forceinline__ void gla_conv8(f32x4 (&out)[8], const bf16_t* Ug, const float* conv, int t0, int s0, int i0, int c0) {
;     ...
;     for (int e = 0; e < 8; ++e) { const int i = i0 + 8 * e; f32x4 a = (f32x4){0.f, 0.f, 0.f, 0.f};
; #pragma unroll
;         for (int j = 0; j < 4; ++j) { const int ds = 3 - j; const float mk = ((s0 + i - ds) >= 0) ? 1.0f : 0.0f; const u32x2 r = raw[e][j];
;             a += (w[j] * mk) * (f32x4){bflo(r.x), bfhi(r.x), bflo(r.y), bfhi(r.y)}; }
; #pragma unroll
;         for (int q = 0; q < 4; ++q) a[q] = a[q] * sigmoidf_(a[q]);
;         out[e] = a; }
	v_lshlrev_b32_e32 v162, 16, v34
	v_and_b32_e32 v163, 0xffff0000, v34
	v_lshlrev_b32_e32 v34, 16, v35
	v_and_b32_e32 v35, 0xffff0000, v35
	v_cndmask_b32_e64 v158, 0, 1.0, vcc
	s_movk_i32 s36, 0xffe8
	v_pk_fma_f32 v[156:157], v[156:157], v[162:163], 0 op_sel_hi:[1,1,0]
	v_pk_fma_f32 v[34:35], v[160:161], v[34:35], 0 op_sel_hi:[1,1,0]
	v_pk_mul_f32 v[160:161], v[158:159], v[12:13] op_sel_hi:[0,1]
	v_pk_mul_f32 v[162:163], v[158:159], v[10:11] op_sel_hi:[0,1]
	s_waitcnt vmcnt(18)
	v_lshlrev_b32_e32 v164, 16, v30
	v_and_b32_e32 v165, 0xffff0000, v30
	v_lshlrev_b32_e32 v30, 16, v31
	v_and_b32_e32 v31, 0xffff0000, v31
	v_cmp_lt_i32_e32 vcc, s36, v159
	v_pk_fma_f32 v[30:31], v[160:161], v[30:31], v[34:35]
	v_pk_fma_f32 v[34:35], v[162:163], v[164:165], v[156:157]
	v_cndmask_b32_e64 v156, 0, 1.0, vcc
	s_movk_i32 s36, 0xffe7
	v_pk_mul_f32 v[160:161], v[156:157], v[8:9] op_sel_hi:[0,1]
	s_waitcnt vmcnt(17)
	v_lshlrev_b32_e32 v162, 16, v28
	v_and_b32_e32 v163, 0xffff0000, v28
	v_lshlrev_b32_e32 v28, 16, v29
	v_and_b32_e32 v29, 0xffff0000, v29
	v_cmp_lt_i32_e32 vcc, s36, v159
	v_mul_f32_e32 v122, 0xbfb8aa3b, v120
	v_mul_f32_e32 v123, 0xbfb8aa3b, v121
	v_pk_mul_f32 v[156:157], v[156:157], v[6:7] op_sel_hi:[0,1]
	v_pk_fma_f32 v[28:29], v[160:161], v[28:29], v[30:31]
	v_cndmask_b32_e64 v30, 0, 1.0, vcc
	v_exp_f32_e32 v122, v122
	v_exp_f32_e32 v123, v123
	v_pk_fma_f32 v[34:35], v[156:157], v[162:163], v[34:35]
	v_pk_mul_f32 v[156:157], v[30:31], v[4:5] op_sel_hi:[0,1]
	v_pk_mul_f32 v[30:31], v[30:31], v[2:3] op_sel_hi:[0,1]
	s_waitcnt vmcnt(16)
	v_lshlrev_b32_e32 v160, 16, v24
	v_and_b32_e32 v161, 0xffff0000, v24
	v_pk_fma_f32 v[160:161], v[30:31], v[160:161], v[34:35]
	v_add_f32_e32 v118, 1.0, v122
	v_mul_f32_e32 v30, 0xbfb8aa3b, v160
	v_exp_f32_e32 v30, v30
	v_mul_f32_e32 v31, 0xbfb8aa3b, v161
	v_add_f32_e32 v119, 1.0, v123
	v_mul_f32_e32 v122, 0xbfb8aa3b, v116
	v_mul_f32_e32 v123, 0xbfb8aa3b, v117
	v_exp_f32_e32 v31, v31
	v_exp_f32_e32 v122, v122
	v_exp_f32_e32 v123, v123
	v_lshlrev_b32_e32 v24, 16, v25
	v_and_b32_e32 v25, 0xffff0000, v25
	v_pk_fma_f32 v[24:25], v[156:157], v[24:25], v[28:29]
	v_add_f32_e32 v28, 1.0, v30
	v_mul_f32_e32 v30, 0xbfb8aa3b, v24
	v_add_f32_e32 v29, 1.0, v31
	v_exp_f32_e32 v30, v30
	v_mul_f32_e32 v31, 0xbfb8aa3b, v25
	v_add_f32_e32 v122, 1.0, v122
	v_add_f32_e32 v123, 1.0, v123
	v_exp_f32_e32 v31, v31
	v_rcp_f32_e32 v122, v122
	v_rcp_f32_e32 v123, v123
	v_rcp_f32_e32 v118, v118
	v_rcp_f32_e32 v119, v119
	v_add_f32_e32 v30, 1.0, v30
	s_movk_i32 s36, 0xffe2
	v_rcp_f32_e32 v156, v30
	v_add_f32_e32 v30, 1.0, v31
	v_cmp_lt_i32_e32 vcc, s36, v159
	v_rcp_f32_e32 v157, v30
	v_pk_mul_f32 v[30:31], v[116:117], v[122:123]
	v_cndmask_b32_e64 v116, 0, 1.0, vcc
	v_pk_mul_f32 v[34:35], v[120:121], v[118:119]
	v_pk_mul_f32 v[118:119], v[116:117], v[16:17] op_sel_hi:[0,1]
	s_waitcnt vmcnt(15)
	v_lshlrev_b32_e32 v120, 16, v114
	v_and_b32_e32 v121, 0xffff0000, v114
	v_lshlrev_b32_e32 v114, 16, v115
	v_and_b32_e32 v115, 0xffff0000, v115
	v_cmp_lt_i32_e32 vcc, s83, v159
	v_pk_mul_f32 v[116:117], v[116:117], v[14:15] op_sel_hi:[0,1]
	v_pk_fma_f32 v[114:115], v[118:119], v[114:115], 0 op_sel_hi:[1,1,0]
	v_cndmask_b32_e64 v118, 0, 1.0, vcc
	s_movk_i32 s36, 0xffe0
	v_pk_fma_f32 v[116:117], v[116:117], v[120:121], 0 op_sel_hi:[1,1,0]
	v_pk_mul_f32 v[120:121], v[118:119], v[12:13] op_sel_hi:[0,1]
	v_pk_mul_f32 v[118:119], v[118:119], v[10:11] op_sel_hi:[0,1]
	s_waitcnt vmcnt(14)
	v_lshlrev_b32_e32 v122, 16, v112
	v_and_b32_e32 v123, 0xffff0000, v112
	v_lshlrev_b32_e32 v112, 16, v113
	v_and_b32_e32 v113, 0xffff0000, v113
	v_cmp_lt_i32_e32 vcc, s36, v159
	v_pk_fma_f32 v[112:113], v[120:121], v[112:113], v[114:115]
	v_pk_fma_f32 v[114:115], v[118:119], v[122:123], v[116:117]
	v_cndmask_b32_e64 v116, 0, 1.0, vcc
	s_movk_i32 s36, 0xffdf
	v_pk_mul_f32 v[118:119], v[116:117], v[8:9] op_sel_hi:[0,1]
	s_waitcnt vmcnt(13)
	v_lshlrev_b32_e32 v120, 16, v110
	v_and_b32_e32 v121, 0xffff0000, v110
	v_lshlrev_b32_e32 v110, 16, v111
	v_and_b32_e32 v111, 0xffff0000, v111
	v_cmp_lt_i32_e32 vcc, s36, v159
	v_pk_mul_f32 v[116:117], v[116:117], v[6:7] op_sel_hi:[0,1]
	v_pk_fma_f32 v[110:111], v[118:119], v[110:111], v[112:113]
	v_cndmask_b32_e64 v112, 0, 1.0, vcc
	s_movk_i32 s36, 0xffda
	v_pk_fma_f32 v[114:115], v[116:117], v[120:121], v[114:115]
	v_pk_mul_f32 v[116:117], v[112:113], v[4:5] op_sel_hi:[0,1]
	s_waitcnt vmcnt(12)
	v_lshlrev_b32_e32 v118, 16, v108
	v_and_b32_e32 v119, 0xffff0000, v108
	v_lshlrev_b32_e32 v108, 16, v109
	v_and_b32_e32 v109, 0xffff0000, v109
	v_cmp_lt_i32_e32 vcc, s36, v159
	v_pk_mul_f32 v[112:113], v[112:113], v[2:3] op_sel_hi:[0,1]
	v_pk_fma_f32 v[108:109], v[116:117], v[108:109], v[110:111]
	v_cndmask_b32_e64 v116, 0, 1.0, vcc
	s_movk_i32 s36, 0xffd9
	v_pk_fma_f32 v[112:113], v[112:113], v[118:119], v[114:115]
	v_pk_mul_f32 v[118:119], v[116:117], v[16:17] op_sel_hi:[0,1]
	s_waitcnt vmcnt(11)
	v_lshlrev_b32_e32 v120, 16, v26
	v_and_b32_e32 v121, 0xffff0000, v26
	v_lshlrev_b32_e32 v26, 16, v27
	v_and_b32_e32 v27, 0xffff0000, v27
	v_cmp_lt_i32_e32 vcc, s36, v159
	v_pk_mul_f32 v[116:117], v[116:117], v[14:15] op_sel_hi:[0,1]
	v_pk_fma_f32 v[26:27], v[118:119], v[26:27], 0 op_sel_hi:[1,1,0]
	v_cndmask_b32_e64 v118, 0, 1.0, vcc
	s_movk_i32 s36, 0xffd8
	v_pk_fma_f32 v[116:117], v[116:117], v[120:121], 0 op_sel_hi:[1,1,0]
	v_pk_mul_f32 v[120:121], v[118:119], v[12:13] op_sel_hi:[0,1]
	v_pk_mul_f32 v[118:119], v[118:119], v[10:11] op_sel_hi:[0,1]
	s_waitcnt vmcnt(10)
; __device__ __forceinline__ float bflo(unsigned w) { return __uint_as_float(w << 16); }
; __device__ __forceinline__ float bfhi(unsigned w) { return __uint_as_float(w & 0xffff0000u); }
; __device__ __forceinline__ float sigmoidf_(float x) { return __builtin_amdgcn_rcpf(1.0f + __expf(-x)); }
; __device__ __forceinline__ void gla_conv8(f32x4 (&out)[8], const bf16_t* Ug, const float* conv, int t0, int s0, int i0, int c0) {
;     ...
;     for (int e = 0; e < 8; ++e) { const int i = i0 + 8 * e; f32x4 a = (f32x4){0.f, 0.f, 0.f, 0.f};
; #pragma unroll
;         for (int j = 0; j < 4; ++j) { const int ds = 3 - j; const float mk = ((s0 + i - ds) >= 0) ? 1.0f : 0.0f; const u32x2 r = raw[e][j];
;             a += (w[j] * mk) * (f32x4){bflo(r.x), bfhi(r.x), bflo(r.y), bfhi(r.y)}; }
; #pragma unroll
;         for (int q = 0; q < 4; ++q) a[q] = a[q] * sigmoidf_(a[q]);
;         out[e] = a; }
	v_lshlrev_b32_e32 v122, 16, v22
	v_and_b32_e32 v123, 0xffff0000, v22
	v_lshlrev_b32_e32 v22, 16, v23
	v_and_b32_e32 v23, 0xffff0000, v23
	v_cmp_lt_i32_e32 vcc, s36, v159
	v_pk_fma_f32 v[22:23], v[120:121], v[22:23], v[26:27]
	v_pk_fma_f32 v[26:27], v[118:119], v[122:123], v[116:117]
	v_cndmask_b32_e64 v116, 0, 1.0, vcc
	s_movk_i32 s36, 0xffd7
	v_pk_mul_f32 v[118:119], v[116:117], v[8:9] op_sel_hi:[0,1]
	s_waitcnt vmcnt(9)
	v_lshlrev_b32_e32 v120, 16, v20
	v_and_b32_e32 v121, 0xffff0000, v20
	v_lshlrev_b32_e32 v20, 16, v21
	v_and_b32_e32 v21, 0xffff0000, v21
	v_cmp_lt_i32_e32 vcc, s36, v159
	v_mul_f32_e32 v114, 0xbfb8aa3b, v112
	v_mul_f32_e32 v115, 0xbfb8aa3b, v113
	v_pk_mul_f32 v[116:117], v[116:117], v[6:7] op_sel_hi:[0,1]
	v_pk_fma_f32 v[20:21], v[118:119], v[20:21], v[22:23]
	v_cndmask_b32_e64 v22, 0, 1.0, vcc
	v_exp_f32_e32 v114, v114
	v_exp_f32_e32 v115, v115
	v_pk_fma_f32 v[26:27], v[116:117], v[120:121], v[26:27]
	v_pk_mul_f32 v[116:117], v[22:23], v[4:5] op_sel_hi:[0,1]
	v_pk_mul_f32 v[22:23], v[22:23], v[2:3] op_sel_hi:[0,1]
	s_waitcnt vmcnt(8)
	v_lshlrev_b32_e32 v118, 16, v18
	v_and_b32_e32 v119, 0xffff0000, v18
	v_pk_fma_f32 v[118:119], v[22:23], v[118:119], v[26:27]
	v_add_f32_e32 v110, 1.0, v114
	v_mul_f32_e32 v22, 0xbfb8aa3b, v118
	v_exp_f32_e32 v22, v22
	v_mul_f32_e32 v23, 0xbfb8aa3b, v119
	v_add_f32_e32 v111, 1.0, v115
	v_mul_f32_e32 v114, 0xbfb8aa3b, v108
	v_mul_f32_e32 v115, 0xbfb8aa3b, v109
	v_exp_f32_e32 v23, v23
	v_exp_f32_e32 v114, v114
	v_exp_f32_e32 v115, v115
	v_lshlrev_b32_e32 v18, 16, v19
	v_and_b32_e32 v19, 0xffff0000, v19
	v_pk_fma_f32 v[18:19], v[116:117], v[18:19], v[20:21]
	v_add_f32_e32 v20, 1.0, v22
	v_mul_f32_e32 v22, 0xbfb8aa3b, v18
	v_add_f32_e32 v21, 1.0, v23
	v_exp_f32_e32 v22, v22
	v_mul_f32_e32 v23, 0xbfb8aa3b, v19
	v_add_f32_e32 v114, 1.0, v114
	v_add_f32_e32 v115, 1.0, v115
	v_exp_f32_e32 v23, v23
	v_rcp_f32_e32 v114, v114
	v_rcp_f32_e32 v115, v115
	v_rcp_f32_e32 v110, v110
	v_rcp_f32_e32 v111, v111
	v_add_f32_e32 v22, 1.0, v22
	s_movk_i32 s36, 0xffd2
	v_rcp_f32_e32 v116, v22
	v_add_f32_e32 v22, 1.0, v23
	v_cmp_lt_i32_e32 vcc, s36, v159
	v_rcp_f32_e32 v117, v22
	v_pk_mul_f32 v[22:23], v[108:109], v[114:115]
	v_cndmask_b32_e64 v108, 0, 1.0, vcc
	s_movk_i32 s36, 0xffd1
	v_pk_mul_f32 v[26:27], v[112:113], v[110:111]
	v_pk_mul_f32 v[110:111], v[108:109], v[16:17] op_sel_hi:[0,1]
	s_waitcnt vmcnt(7)
	v_lshlrev_b32_e32 v112, 16, v56
	v_and_b32_e32 v113, 0xffff0000, v56
	v_lshlrev_b32_e32 v56, 16, v57
	v_and_b32_e32 v57, 0xffff0000, v57
	v_cmp_lt_i32_e32 vcc, s36, v159
	v_pk_mul_f32 v[108:109], v[108:109], v[14:15] op_sel_hi:[0,1]
	v_pk_fma_f32 v[56:57], v[110:111], v[56:57], 0 op_sel_hi:[1,1,0]
	v_cndmask_b32_e64 v110, 0, 1.0, vcc
	s_movk_i32 s36, 0xffd0
	v_pk_fma_f32 v[108:109], v[108:109], v[112:113], 0 op_sel_hi:[1,1,0]
	v_pk_mul_f32 v[112:113], v[110:111], v[12:13] op_sel_hi:[0,1]
	v_pk_mul_f32 v[110:111], v[110:111], v[10:11] op_sel_hi:[0,1]
	s_waitcnt vmcnt(6)
	v_lshlrev_b32_e32 v114, 16, v54
	v_and_b32_e32 v115, 0xffff0000, v54
	v_lshlrev_b32_e32 v54, 16, v55
	v_and_b32_e32 v55, 0xffff0000, v55
	v_cmp_lt_i32_e32 vcc, s36, v159
	v_pk_fma_f32 v[54:55], v[112:113], v[54:55], v[56:57]
	v_pk_fma_f32 v[56:57], v[110:111], v[114:115], v[108:109]
	v_cndmask_b32_e64 v108, 0, 1.0, vcc
	s_movk_i32 s36, 0xffcf
	v_pk_mul_f32 v[110:111], v[108:109], v[8:9] op_sel_hi:[0,1]
	s_waitcnt vmcnt(5)
	v_lshlrev_b32_e32 v112, 16, v52
	v_and_b32_e32 v113, 0xffff0000, v52
	v_lshlrev_b32_e32 v52, 16, v53
	v_and_b32_e32 v53, 0xffff0000, v53
	v_cmp_lt_i32_e32 vcc, s36, v159
	v_pk_mul_f32 v[108:109], v[108:109], v[6:7] op_sel_hi:[0,1]
	v_pk_fma_f32 v[52:53], v[110:111], v[52:53], v[54:55]
	v_cndmask_b32_e64 v54, 0, 1.0, vcc
	s_movk_i32 s36, 0xffca
	v_pk_fma_f32 v[56:57], v[108:109], v[112:113], v[56:57]
	v_pk_mul_f32 v[108:109], v[54:55], v[4:5] op_sel_hi:[0,1]
	s_waitcnt vmcnt(4)
	v_lshlrev_b32_e32 v110, 16, v48
	v_and_b32_e32 v111, 0xffff0000, v48
	v_lshlrev_b32_e32 v48, 16, v49
	v_and_b32_e32 v49, 0xffff0000, v49
	v_cmp_lt_i32_e32 vcc, s36, v159
	v_pk_fma_f32 v[48:49], v[108:109], v[48:49], v[52:53]
	s_movk_i32 s36, 0xffc9
	v_cndmask_b32_e64 v108, 0, 1.0, vcc
	v_pk_mul_f32 v[16:17], v[108:109], v[16:17] op_sel_hi:[0,1]
	v_pk_mul_f32 v[14:15], v[108:109], v[14:15] op_sel_hi:[0,1]
	s_waitcnt vmcnt(3)
	v_lshlrev_b32_e32 v108, 16, v46
	v_and_b32_e32 v109, 0xffff0000, v46
	v_lshlrev_b32_e32 v46, 16, v47
	v_and_b32_e32 v47, 0xffff0000, v47
	v_cmp_lt_i32_e32 vcc, s36, v159
	v_pk_fma_f32 v[16:17], v[16:17], v[46:47], 0 op_sel_hi:[1,1,0]
	s_movk_i32 s36, 0xffc8
	v_cndmask_b32_e64 v46, 0, 1.0, vcc
	v_pk_fma_f32 v[14:15], v[14:15], v[108:109], 0 op_sel_hi:[1,1,0]
	v_pk_mul_f32 v[12:13], v[46:47], v[12:13] op_sel_hi:[0,1]
	v_pk_mul_f32 v[10:11], v[46:47], v[10:11] op_sel_hi:[0,1]
	s_waitcnt vmcnt(2)
; __device__ __forceinline__ bf16_t f2bf(float x) { return (bf16_t)(cvt_pk_bf16(x, 0.f) & 0xffffu); }
; __device__ __forceinline__ float bflo(unsigned w) { return __uint_as_float(w << 16); }
; __device__ __forceinline__ float bfhi(unsigned w) { return __uint_as_float(w & 0xffff0000u); }
; __device__ __forceinline__ float sigmoidf_(float x) { return __builtin_amdgcn_rcpf(1.0f + __expf(-x)); }
; __device__ __forceinline__ void gla_conv8(f32x4 (&out)[8], const bf16_t* Ug, const float* conv, int t0, int s0, int i0, int c0) {
;     ...
;     for (int e = 0; e < 8; ++e) { const int i = i0 + 8 * e; f32x4 a = (f32x4){0.f, 0.f, 0.f, 0.f};
; #pragma unroll
;         for (int j = 0; j < 4; ++j) { const int ds = 3 - j; const float mk = ((s0 + i - ds) >= 0) ? 1.0f : 0.0f; const u32x2 r = raw[e][j];
;             a += (w[j] * mk) * (f32x4){bflo(r.x), bfhi(r.x), bflo(r.y), bfhi(r.y)}; }
; #pragma unroll
;         for (int q = 0; q < 4; ++q) a[q] = a[q] * sigmoidf_(a[q]);
;         out[e] = a; }
; __device__ __forceinline__ void gla_c_tile(LAS unsigned char* lds, const GlaArgs& A, int tile, int tid) {
;     ...
;       else { const int ev = cc - 128;
; #pragma unroll
;           for (int e = 0; e < 8; ++e) { const int i = i0 + 8 * e;
; #pragma unroll
;               for (int q = 0; q < 4; ++q) VT[(ev + q) * 72 + i] = f2bf(o[e][q]); } } }
	v_lshlrev_b32_e32 v46, 16, v44
	v_and_b32_e32 v47, 0xffff0000, v44
	v_cmp_lt_i32_e32 vcc, s36, v159
	v_pk_fma_f32 v[10:11], v[10:11], v[46:47], v[14:15]
	s_movk_i32 s36, 0xffc7
	v_cndmask_b32_e64 v14, 0, 1.0, vcc
	v_pk_mul_f32 v[8:9], v[14:15], v[8:9] op_sel_hi:[0,1]
	v_pk_mul_f32 v[6:7], v[14:15], v[6:7] op_sel_hi:[0,1]
	s_waitcnt vmcnt(1)
	v_lshlrev_b32_e32 v14, 16, v42
	v_and_b32_e32 v15, 0xffff0000, v42
	v_cmp_lt_i32_e32 vcc, s36, v159
	v_pk_fma_f32 v[6:7], v[6:7], v[14:15], v[10:11]
	v_pk_mul_f32 v[54:55], v[54:55], v[2:3] op_sel_hi:[0,1]
	v_cndmask_b32_e64 v10, 0, 1.0, vcc
	v_pk_mul_f32 v[4:5], v[10:11], v[4:5] op_sel_hi:[0,1]
	v_pk_mul_f32 v[2:3], v[10:11], v[2:3] op_sel_hi:[0,1]
	s_waitcnt vmcnt(0)
	v_lshlrev_b32_e32 v10, 16, v40
	v_and_b32_e32 v11, 0xffff0000, v40
	v_pk_fma_f32 v[2:3], v[2:3], v[10:11], v[6:7]
	v_pk_fma_f32 v[54:55], v[54:55], v[110:111], v[56:57]
	v_mul_f32_e32 v6, 0xbfb8aa3b, v2
	v_mul_f32_e32 v56, 0xbfb8aa3b, v54
	v_mul_f32_e32 v57, 0xbfb8aa3b, v55
	v_lshlrev_b32_e32 v44, 16, v45
	v_and_b32_e32 v45, 0xffff0000, v45
	v_exp_f32_e32 v6, v6
	v_mul_f32_e32 v7, 0xbfb8aa3b, v3
	v_exp_f32_e32 v56, v56
	v_exp_f32_e32 v57, v57
	v_pk_fma_f32 v[12:13], v[12:13], v[44:45], v[16:17]
	v_lshlrev_b32_e32 v16, 16, v43
	v_and_b32_e32 v17, 0xffff0000, v43
	v_exp_f32_e32 v7, v7
	v_pk_fma_f32 v[8:9], v[8:9], v[16:17], v[12:13]
	v_lshlrev_b32_e32 v12, 16, v41
	v_and_b32_e32 v13, 0xffff0000, v41
	v_pk_fma_f32 v[10:11], v[4:5], v[12:13], v[8:9]
	v_add_f32_e32 v4, 1.0, v6
	v_mul_f32_e32 v6, 0xbfb8aa3b, v10
	v_add_f32_e32 v52, 1.0, v56
	v_add_f32_e32 v53, 1.0, v57
	v_mul_f32_e32 v56, 0xbfb8aa3b, v48
	v_mul_f32_e32 v57, 0xbfb8aa3b, v49
	v_add_f32_e32 v5, 1.0, v7
	v_exp_f32_e32 v6, v6
	v_mul_f32_e32 v7, 0xbfb8aa3b, v11
	v_exp_f32_e32 v56, v56
	v_exp_f32_e32 v57, v57
	v_exp_f32_e32 v7, v7
	v_add_f32_e32 v6, 1.0, v6
	v_add_f32_e32 v56, 1.0, v56
	v_add_f32_e32 v57, 1.0, v57
	v_rcp_f32_e32 v12, v6
	v_add_f32_e32 v6, 1.0, v7
	v_rcp_f32_e32 v36, v36
	v_rcp_f32_e32 v37, v37
	v_rcp_f32_e32 v28, v28
	v_rcp_f32_e32 v29, v29
	v_rcp_f32_e32 v20, v20
	v_rcp_f32_e32 v21, v21
	v_rcp_f32_e32 v52, v52
	v_rcp_f32_e32 v53, v53
	v_rcp_f32_e32 v56, v56
	v_rcp_f32_e32 v57, v57
	v_rcp_f32_e32 v4, v4
	v_rcp_f32_e32 v5, v5
	v_rcp_f32_e32 v13, v6
	v_pk_mul_f32 v[36:37], v[168:169], v[36:37]
	v_pk_mul_f32 v[32:33], v[32:33], v[166:167]
	v_pk_mul_f32 v[28:29], v[160:161], v[28:29]
	v_pk_mul_f32 v[24:25], v[24:25], v[156:157]
	v_pk_mul_f32 v[20:21], v[118:119], v[20:21]
	v_pk_mul_f32 v[18:19], v[18:19], v[116:117]
	v_pk_mul_f32 v[8:9], v[54:55], v[52:53]
	v_pk_mul_f32 v[6:7], v[48:49], v[56:57]
	v_pk_mul_f32 v[4:5], v[2:3], v[4:5]
	v_pk_mul_f32 v[2:3], v[10:11], v[12:13]
	s_and_saveexec_b64 s[38:39], s[16:17]
	s_xor_b64 s[38:39], exec, s[38:39]
	s_cbranch_execz .LBB0_312
	v_cvt_pk_bf16_f32 v10, v50, s0
	ds_write_b16 v146, v10 offset:35072
	v_cvt_pk_bf16_f32 v10, v51, s0
	ds_write_b16 v146, v10 offset:35216
	v_cvt_pk_bf16_f32 v10, v38, s0
	ds_write_b16 v146, v10 offset:35360
	v_cvt_pk_bf16_f32 v10, v39, s0
	ds_write_b16 v146, v10 offset:35504
	v_cvt_pk_bf16_f32 v10, v36, s0
	ds_write_b16 v146, v10 offset:35088
	v_cvt_pk_bf16_f32 v10, v37, s0
	ds_write_b16 v146, v10 offset:35232
	v_cvt_pk_bf16_f32 v10, v32, s0
	ds_write_b16 v146, v10 offset:35376
	v_cvt_pk_bf16_f32 v10, v33, s0
	ds_write_b16 v146, v10 offset:35520
	v_cvt_pk_bf16_f32 v10, v34, s0
	ds_write_b16 v146, v10 offset:35104
	v_cvt_pk_bf16_f32 v10, v35, s0
	ds_write_b16 v146, v10 offset:35248
	v_cvt_pk_bf16_f32 v10, v30, s0
	ds_write_b16 v146, v10 offset:35392
	v_cvt_pk_bf16_f32 v10, v31, s0
	ds_write_b16 v146, v10 offset:35536
	v_cvt_pk_bf16_f32 v10, v28, s0
	ds_write_b16 v146, v10 offset:35120
	v_cvt_pk_bf16_f32 v10, v29, s0
	ds_write_b16 v146, v10 offset:35264
	v_cvt_pk_bf16_f32 v10, v24, s0
	ds_write_b16 v146, v10 offset:35408
	v_cvt_pk_bf16_f32 v10, v25, s0
	ds_write_b16 v146, v10 offset:35552
	v_cvt_pk_bf16_f32 v10, v26, s0
	ds_write_b16 v146, v10 offset:35136
	v_cvt_pk_bf16_f32 v10, v27, s0
	ds_write_b16 v146, v10 offset:35280
	v_cvt_pk_bf16_f32 v10, v22, s0
	ds_write_b16 v146, v10 offset:35424
	v_cvt_pk_bf16_f32 v10, v23, s0
	ds_write_b16 v146, v10 offset:35568
	v_cvt_pk_bf16_f32 v10, v20, s0
	ds_write_b16 v146, v10 offset:35152
	v_cvt_pk_bf16_f32 v10, v21, s0
	ds_write_b16 v146, v10 offset:35296
	v_cvt_pk_bf16_f32 v10, v18, s0
	v_cvt_pk_bf16_f32 v8, v8, s0
	v_cvt_pk_bf16_f32 v6, v6, s0
	v_cvt_pk_bf16_f32 v4, v4, s0
	v_cvt_pk_bf16_f32 v2, v2, s0
	ds_write_b16 v146, v10 offset:35440
	v_cvt_pk_bf16_f32 v10, v19, s0
	ds_write_b16 v146, v8 offset:35168
	v_cvt_pk_bf16_f32 v8, v9, s0
	ds_write_b16 v146, v6 offset:35456
	v_cvt_pk_bf16_f32 v6, v7, s0
	ds_write_b16 v146, v4 offset:35184
	v_cvt_pk_bf16_f32 v4, v5, s0
	ds_write_b16 v146, v2 offset:35472
	v_cvt_pk_bf16_f32 v2, v3, s0
	ds_write_b16 v146, v10 offset:35584
	ds_write_b16 v146, v8 offset:35312
	ds_write_b16 v146, v6 offset:35600
	ds_write_b16 v146, v4 offset:35328
	ds_write_b16 v146, v2 offset:35616
